# v19: v17 plus nt policy on the streamed log-decay and gated-input loads of the RG-LRU scan
# speedup vs baseline: 1.0584x; 1.0584x over previous
.LBB0_1706:
	v_add_u32_e32 v66, 0xffffe800, v88
	v_lshl_add_u64 v[34:35], s[18:19], 0, v[66:67]
	v_add_u32_e32 v66, 0xfffff000, v88
	v_lshl_add_u64 v[36:37], s[18:19], 0, v[66:67]
	v_add_u32_e32 v66, 0xfffff800, v88
	global_load_dwordx4 v[58:61], v[34:35], off nt
	global_load_dwordx4 v[54:57], v[36:37], off nt
	v_lshl_add_u64 v[34:35], s[18:19], 0, v[66:67]
	v_mov_b32_e32 v89, v67
	v_lshl_add_u64 v[36:37], s[18:19], 0, v[88:89]
	global_load_dwordx4 v[50:53], v[34:35], off nt
	global_load_dwordx4 v[42:45], v[36:37], off nt
	global_load_dwordx2 v[106:107], v[90:91], off nt
	global_load_dwordx2 v[108:109], v[90:91], off offset:1024 nt
	global_load_dwordx2 v[110:111], v[90:91], off offset:2048 nt
	global_load_dwordx2 v[112:113], v[90:91], off offset:3072 nt
	s_add_i32 s5, s6, 2
	s_cmp_lt_u32 s6, 14
	s_cselect_b64 s[0:1], -1, 0
	s_and_b64 vcc, s[0:1], exec
	s_cselect_b32 s0, s4, 60
	v_lshl_add_u32 v66, s0, 11, v68
	v_lshl_add_u64 v[34:35], s[18:19], 0, v[66:67]
	v_lshl_add_u32 v66, s0, 10, v70
	s_or_b32 s1, s0, 1
	v_lshl_add_u64 v[38:39], s[24:25], 0, v[66:67]
	v_lshl_add_u32 v66, s1, 11, v68
	s_waitcnt vmcnt(0) lgkmcnt(0)
	v_cvt_pk_f32_fp8_e32 v[150:151], v86
	v_cvt_pk_f32_fp8_sdwa v[134:135], v86 src0_sel:WORD_1
	v_cvt_pk_f32_fp8_e32 v[118:119], v87
	v_cvt_pk_f32_fp8_sdwa v[102:103], v87 src0_sel:WORD_1
	global_load_dwordx4 v[34:37], v[34:35], off nt
	v_cvt_pk_f32_fp8_e32 v[152:153], v92
	global_load_dwordx2 v[86:87], v[38:39], off nt
	v_lshl_add_u64 v[38:39], s[18:19], 0, v[66:67]
	v_lshl_add_u32 v66, s1, 10, v70
	s_or_b32 s1, s0, 2
	v_lshl_add_u64 v[46:47], s[24:25], 0, v[66:67]
	v_lshl_add_u32 v66, s1, 11, v68
	v_cvt_pk_f32_fp8_sdwa v[136:137], v92 src0_sel:WORD_1
	v_cvt_pk_f32_fp8_e32 v[120:121], v93
	v_cvt_pk_f32_fp8_sdwa v[104:105], v93 src0_sel:WORD_1
	global_load_dwordx4 v[38:41], v[38:39], off nt
	s_or_b32 s0, s0, 3
	global_load_dwordx2 v[92:93], v[46:47], off nt
	v_lshl_add_u64 v[46:47], s[18:19], 0, v[66:67]
	v_lshl_add_u32 v66, s1, 10, v70
	v_lshl_add_u64 v[62:63], s[24:25], 0, v[66:67]
	v_lshl_add_u32 v66, s0, 11, v68
	v_cvt_pk_f32_fp8_e32 v[146:147], v94
	v_cvt_pk_f32_fp8_sdwa v[130:131], v94 src0_sel:WORD_1
	v_cvt_pk_f32_fp8_e32 v[114:115], v95
	v_cvt_pk_f32_fp8_sdwa v[98:99], v95 src0_sel:WORD_1
	global_load_dwordx4 v[46:49], v[46:47], off nt
	v_cvt_pk_f32_fp8_e32 v[148:149], v96
	global_load_dwordx2 v[94:95], v[62:63], off nt
	v_lshl_add_u64 v[62:63], s[18:19], 0, v[66:67]
	v_lshl_add_u32 v66, s0, 10, v70
	v_cvt_pk_f32_fp8_sdwa v[132:133], v96 src0_sel:WORD_1
	v_cvt_pk_f32_fp8_e32 v[116:117], v97
	v_cvt_pk_f32_fp8_sdwa v[100:101], v97 src0_sel:WORD_1
	v_lshl_add_u64 v[96:97], s[24:25], 0, v[66:67]
	global_load_dwordx4 v[62:65], v[62:63], off nt
	s_nop 0
	global_load_dwordx2 v[96:97], v[96:97], off nt
	v_lshlrev_b32_e32 v162, 16, v30
	v_and_b32_e32 v163, 0xffff0000, v30
	v_mul_f32_e32 v30, 0x3fb8aa3b, v162
	v_exp_f32_e32 v164, v30
	v_mul_f32_e32 v30, 0x3fb8aa3b, v163
	v_pk_add_f32 v[10:11], v[10:11], v[162:163]
	v_lshlrev_b32_e32 v162, 16, v26
	v_exp_f32_e32 v165, v30
	v_and_b32_e32 v163, 0xffff0000, v26
	v_mul_f32_e32 v26, 0x3fb8aa3b, v162
	v_exp_f32_e32 v176, v26
	v_mul_f32_e32 v26, 0x3fb8aa3b, v163
	v_exp_f32_e32 v177, v26
	v_pk_add_f32 v[10:11], v[10:11], v[162:163]
	v_lshlrev_b32_e32 v162, 16, v22
	v_and_b32_e32 v163, 0xffff0000, v22
	v_pk_fma_f32 v[14:15], v[14:15], v[164:165], v[150:151]
	v_lshlrev_b32_e32 v150, 16, v18
	v_pk_add_f32 v[10:11], v[10:11], v[162:163]
	v_and_b32_e32 v151, 0xffff0000, v18
	v_mul_f32_e32 v18, 0x3fb8aa3b, v150
	v_pk_fma_f32 v[14:15], v[176:177], v[14:15], v[152:153]
	v_exp_f32_e32 v152, v18
	v_mul_f32_e32 v18, 0x3fb8aa3b, v151
	v_pk_add_f32 v[10:11], v[10:11], v[150:151]
	v_lshlrev_b32_e32 v150, 16, v58
	v_exp_f32_e32 v153, v18
	v_and_b32_e32 v151, 0xffff0000, v58
	v_mul_f32_e32 v18, 0x3fb8aa3b, v150
	v_mul_f32_e32 v22, 0x3fb8aa3b, v162
	v_exp_f32_e32 v162, v18
	v_mul_f32_e32 v18, 0x3fb8aa3b, v151
	v_pk_add_f32 v[10:11], v[10:11], v[150:151]
	v_lshlrev_b32_e32 v150, 16, v54
	v_exp_f32_e32 v178, v22
	v_mul_f32_e32 v22, 0x3fb8aa3b, v163
	v_exp_f32_e32 v163, v18
	v_and_b32_e32 v151, 0xffff0000, v54
	v_mul_f32_e32 v18, 0x3fb8aa3b, v150
	v_exp_f32_e32 v164, v18
	v_mul_f32_e32 v18, 0x3fb8aa3b, v151
	v_pk_add_f32 v[10:11], v[10:11], v[150:151]
	v_lshlrev_b32_e32 v150, 16, v50
	v_exp_f32_e32 v165, v18
	v_and_b32_e32 v151, 0xffff0000, v50
	v_mul_f32_e32 v18, 0x3fb8aa3b, v150
	v_exp_f32_e32 v179, v22
	v_exp_f32_e32 v176, v18
	v_mul_f32_e32 v18, 0x3fb8aa3b, v151
	v_pk_add_f32 v[10:11], v[10:11], v[150:151]
	v_lshlrev_b32_e32 v150, 16, v42
	v_exp_f32_e32 v177, v18
	v_and_b32_e32 v151, 0xffff0000, v42
	v_mul_f32_e32 v18, 0x3fb8aa3b, v150
	v_exp_f32_e32 v180, v18
	v_mul_f32_e32 v18, 0x3fb8aa3b, v151
	v_lshlrev_b32_e32 v30, 16, v31
	v_exp_f32_e32 v181, v18
	v_and_b32_e32 v31, 0xffff0000, v31
	v_mul_f32_e32 v18, 0x3fb8aa3b, v30
	v_pk_fma_f32 v[14:15], v[178:179], v[14:15], v[146:147]
	v_exp_f32_e32 v146, v18
	v_mul_f32_e32 v18, 0x3fb8aa3b, v31
	v_lshlrev_b32_e32 v26, 16, v27
	v_exp_f32_e32 v147, v18
	v_and_b32_e32 v27, 0xffff0000, v27
	v_mul_f32_e32 v18, 0x3fb8aa3b, v26
	v_pk_add_f32 v[12:13], v[12:13], v[30:31]
	v_exp_f32_e32 v30, v18
	v_mul_f32_e32 v18, 0x3fb8aa3b, v27
	v_lshlrev_b32_e32 v22, 16, v23
	v_exp_f32_e32 v31, v18
	v_and_b32_e32 v23, 0xffff0000, v23
	v_mul_f32_e32 v18, 0x3fb8aa3b, v22
	v_pk_add_f32 v[12:13], v[12:13], v[26:27]
	v_exp_f32_e32 v26, v18
	v_mul_f32_e32 v18, 0x3fb8aa3b, v23
	v_exp_f32_e32 v27, v18
	v_pk_add_f32 v[12:13], v[12:13], v[22:23]
	v_lshlrev_b32_e32 v18, 16, v19
	v_and_b32_e32 v19, 0xffff0000, v19
	v_pk_fma_f32 v[16:17], v[16:17], v[146:147], v[134:135]
	v_mul_f32_e32 v22, 0x3fb8aa3b, v18
	v_mul_f32_e32 v23, 0x3fb8aa3b, v19
	v_pk_add_f32 v[12:13], v[12:13], v[18:19]
	v_lshlrev_b32_e32 v18, 16, v59
	v_and_b32_e32 v19, 0xffff0000, v59
	v_pk_fma_f32 v[16:17], v[30:31], v[16:17], v[136:137]
	v_mul_f32_e32 v30, 0x3fb8aa3b, v18
	v_pk_add_f32 v[12:13], v[12:13], v[18:19]
	v_lshlrev_b32_e32 v18, 16, v55
	v_mul_f32_e32 v31, 0x3fb8aa3b, v19
	v_and_b32_e32 v19, 0xffff0000, v55
	v_mul_f32_e32 v42, 0x3fb8aa3b, v18
	v_exp_f32_e32 v22, v22
	v_exp_f32_e32 v23, v23
	v_exp_f32_e32 v54, v42
	v_mul_f32_e32 v42, 0x3fb8aa3b, v19
	v_pk_add_f32 v[12:13], v[12:13], v[18:19]
	v_lshlrev_b32_e32 v18, 16, v51
	v_exp_f32_e32 v55, v42
	v_and_b32_e32 v19, 0xffff0000, v51
	v_mul_f32_e32 v42, 0x3fb8aa3b, v18
	v_exp_f32_e32 v50, v42
	v_mul_f32_e32 v42, 0x3fb8aa3b, v19
	v_pk_add_f32 v[12:13], v[12:13], v[18:19]
	v_lshlrev_b32_e32 v18, 16, v43
	v_and_b32_e32 v19, 0xffff0000, v43
	v_exp_f32_e32 v51, v42
	v_mul_f32_e32 v42, 0x3fb8aa3b, v18
	v_mul_f32_e32 v43, 0x3fb8aa3b, v19
	v_pk_fma_f32 v[16:17], v[26:27], v[16:17], v[130:131]
	v_pk_add_f32 v[12:13], v[12:13], v[18:19]
	v_lshlrev_b32_e32 v18, 16, v32
	v_and_b32_e32 v19, 0xffff0000, v32
	v_cvt_pk_f32_fp8_sdwa v[138:139], v106 src0_sel:WORD_1
	v_exp_f32_e32 v30, v30
	v_exp_f32_e32 v31, v31
	v_pk_fma_f32 v[16:17], v[22:23], v[16:17], v[132:133]
	v_mul_f32_e32 v22, 0x3fb8aa3b, v18
	v_mul_f32_e32 v23, 0x3fb8aa3b, v19
	v_exp_f32_e32 v22, v22
	v_exp_f32_e32 v23, v23
	v_pk_add_f32 v[6:7], v[6:7], v[18:19]
	v_lshlrev_b32_e32 v18, 16, v28
	v_and_b32_e32 v19, 0xffff0000, v28
	v_mul_f32_e32 v26, 0x3fb8aa3b, v18
	v_mul_f32_e32 v27, 0x3fb8aa3b, v19
	v_pk_add_f32 v[6:7], v[6:7], v[18:19]
	v_lshlrev_b32_e32 v18, 16, v24
	v_and_b32_e32 v19, 0xffff0000, v24
	v_cvt_pk_f32_fp8_sdwa v[140:141], v108 src0_sel:WORD_1
	v_exp_f32_e32 v26, v26
	v_exp_f32_e32 v27, v27
	v_mul_f32_e32 v24, 0x3fb8aa3b, v18
	v_pk_add_f32 v[6:7], v[6:7], v[18:19]
	v_lshlrev_b32_e32 v18, 16, v20
	v_cvt_pk_f32_fp8_sdwa v[142:143], v110 src0_sel:WORD_1
	v_pk_fma_f32 v[16:17], v[30:31], v[16:17], v[138:139]
	v_exp_f32_e32 v30, v24
	v_mul_f32_e32 v24, 0x3fb8aa3b, v19
	v_and_b32_e32 v19, 0xffff0000, v20
	v_mul_f32_e32 v20, 0x3fb8aa3b, v18
	v_cvt_pk_f32_fp8_sdwa v[144:145], v112 src0_sel:WORD_1
	v_exp_f32_e32 v42, v42
	v_exp_f32_e32 v43, v43
	v_pk_fma_f32 v[2:3], v[2:3], v[22:23], v[118:119]
	v_exp_f32_e32 v22, v20
	v_mul_f32_e32 v20, 0x3fb8aa3b, v19
	v_pk_add_f32 v[6:7], v[6:7], v[18:19]
	v_lshlrev_b32_e32 v18, 16, v60
	v_exp_f32_e32 v23, v20
	v_and_b32_e32 v19, 0xffff0000, v60
	v_mul_f32_e32 v20, 0x3fb8aa3b, v18
	v_pk_fma_f32 v[16:17], v[54:55], v[16:17], v[140:141]
	v_pk_fma_f32 v[2:3], v[26:27], v[2:3], v[120:121]
	v_exp_f32_e32 v26, v20
	v_mul_f32_e32 v20, 0x3fb8aa3b, v19
	v_pk_add_f32 v[6:7], v[6:7], v[18:19]
	v_lshlrev_b32_e32 v18, 16, v56
	v_pk_fma_f32 v[16:17], v[50:51], v[16:17], v[142:143]
	v_exp_f32_e32 v27, v20
	v_and_b32_e32 v19, 0xffff0000, v56
	v_mul_f32_e32 v20, 0x3fb8aa3b, v18
	v_pk_fma_f32 v[16:17], v[42:43], v[16:17], v[144:145]
	v_exp_f32_e32 v42, v20
	v_mul_f32_e32 v20, 0x3fb8aa3b, v19
	v_pk_add_f32 v[6:7], v[6:7], v[18:19]
	v_lshlrev_b32_e32 v18, 16, v52
	v_exp_f32_e32 v31, v24
	v_exp_f32_e32 v43, v20
	v_and_b32_e32 v19, 0xffff0000, v52
	v_mul_f32_e32 v20, 0x3fb8aa3b, v18
	v_exp_f32_e32 v50, v20
	v_mul_f32_e32 v20, 0x3fb8aa3b, v19
	v_pk_add_f32 v[6:7], v[6:7], v[18:19]
	v_lshlrev_b32_e32 v18, 16, v44
	v_exp_f32_e32 v51, v20
	v_and_b32_e32 v19, 0xffff0000, v44
	v_mul_f32_e32 v20, 0x3fb8aa3b, v18
	v_cvt_pk_f32_fp8_e32 v[122:123], v107
	v_exp_f32_e32 v54, v20
	v_mul_f32_e32 v20, 0x3fb8aa3b, v19
	v_pk_add_f32 v[6:7], v[6:7], v[18:19]
	v_lshlrev_b32_e32 v18, 16, v33
	v_exp_f32_e32 v55, v20
	v_pk_fma_f32 v[2:3], v[30:31], v[2:3], v[114:115]
	v_and_b32_e32 v19, 0xffff0000, v33
	v_mul_f32_e32 v20, 0x3fb8aa3b, v18
	v_pk_fma_f32 v[2:3], v[22:23], v[2:3], v[116:117]
	v_exp_f32_e32 v22, v20
	v_mul_f32_e32 v20, 0x3fb8aa3b, v19
	v_pk_add_f32 v[8:9], v[8:9], v[18:19]
	v_lshlrev_b32_e32 v18, 16, v29
	v_exp_f32_e32 v23, v20
	v_and_b32_e32 v19, 0xffff0000, v29
	v_mul_f32_e32 v20, 0x3fb8aa3b, v18
	v_pk_fma_f32 v[2:3], v[26:27], v[2:3], v[122:123]
	v_exp_f32_e32 v26, v20
	v_mul_f32_e32 v20, 0x3fb8aa3b, v19
	v_pk_add_f32 v[8:9], v[8:9], v[18:19]
	v_lshlrev_b32_e32 v18, 16, v25
	v_exp_f32_e32 v27, v20
	v_and_b32_e32 v19, 0xffff0000, v25
	v_mul_f32_e32 v20, 0x3fb8aa3b, v18
	v_exp_f32_e32 v24, v20
	v_mul_f32_e32 v20, 0x3fb8aa3b, v19
	v_pk_add_f32 v[8:9], v[8:9], v[18:19]
	v_lshlrev_b32_e32 v18, 16, v21
	v_and_b32_e32 v19, 0xffff0000, v21
	v_exp_f32_e32 v25, v20
	v_mul_f32_e32 v20, 0x3fb8aa3b, v18
	v_mul_f32_e32 v21, 0x3fb8aa3b, v19
	v_pk_add_f32 v[8:9], v[8:9], v[18:19]
	v_lshlrev_b32_e32 v18, 16, v61
	v_and_b32_e32 v19, 0xffff0000, v61
	v_pk_fma_f32 v[4:5], v[4:5], v[22:23], v[102:103]
	v_exp_f32_e32 v20, v20
	v_exp_f32_e32 v21, v21
	v_mul_f32_e32 v22, 0x3fb8aa3b, v18
	v_mul_f32_e32 v23, 0x3fb8aa3b, v19
	v_pk_add_f32 v[8:9], v[8:9], v[18:19]
	v_lshlrev_b32_e32 v18, 16, v57
	v_and_b32_e32 v19, 0xffff0000, v57
	v_cvt_pk_f32_fp8_e32 v[154:155], v106
	v_cvt_pk_f32_fp8_sdwa v[106:107], v107 src0_sel:WORD_1
	v_pk_fma_f32 v[4:5], v[26:27], v[4:5], v[104:105]
	v_exp_f32_e32 v22, v22
	v_exp_f32_e32 v23, v23
	v_mul_f32_e32 v26, 0x3fb8aa3b, v18
	v_mul_f32_e32 v27, 0x3fb8aa3b, v19
	v_pk_add_f32 v[8:9], v[8:9], v[18:19]
	v_lshlrev_b32_e32 v18, 16, v53
	v_and_b32_e32 v19, 0xffff0000, v53
	v_cvt_pk_f32_fp8_e32 v[156:157], v108
	v_cvt_pk_f32_fp8_e32 v[124:125], v109
	v_cvt_pk_f32_fp8_sdwa v[108:109], v109 src0_sel:WORD_1
	v_exp_f32_e32 v26, v26
	v_exp_f32_e32 v27, v27
	v_mul_f32_e32 v28, 0x3fb8aa3b, v18
	v_mul_f32_e32 v29, 0x3fb8aa3b, v19
	v_pk_add_f32 v[8:9], v[8:9], v[18:19]
	v_lshlrev_b32_e32 v18, 16, v45
	v_and_b32_e32 v19, 0xffff0000, v45
	v_cvt_pk_f32_fp8_e32 v[158:159], v110
	v_cvt_pk_f32_fp8_e32 v[126:127], v111
	v_cvt_pk_f32_fp8_sdwa v[110:111], v111 src0_sel:WORD_1
	v_exp_f32_e32 v28, v28
	v_exp_f32_e32 v29, v29
	v_mul_f32_e32 v30, 0x3fb8aa3b, v18
	v_mul_f32_e32 v31, 0x3fb8aa3b, v19
	v_pk_fma_f32 v[4:5], v[24:25], v[4:5], v[98:99]
	v_cvt_pk_f32_fp8_e32 v[160:161], v112
	v_cvt_pk_f32_fp8_e32 v[128:129], v113
	v_cvt_pk_f32_fp8_sdwa v[112:113], v113 src0_sel:WORD_1
	v_exp_f32_e32 v30, v30
	v_exp_f32_e32 v31, v31
	v_pk_fma_f32 v[4:5], v[20:21], v[4:5], v[100:101]
	v_pk_fma_f32 v[14:15], v[152:153], v[14:15], v[148:149]
	v_pk_fma_f32 v[4:5], v[22:23], v[4:5], v[106:107]
	v_pk_fma_f32 v[14:15], v[162:163], v[14:15], v[154:155]
	v_pk_fma_f32 v[4:5], v[26:27], v[4:5], v[108:109]
	v_pk_fma_f32 v[14:15], v[164:165], v[14:15], v[156:157]
	v_pk_fma_f32 v[2:3], v[42:43], v[2:3], v[124:125]
	v_pk_fma_f32 v[4:5], v[28:29], v[4:5], v[110:111]
	v_pk_fma_f32 v[14:15], v[176:177], v[14:15], v[158:159]
	v_pk_fma_f32 v[2:3], v[50:51], v[2:3], v[126:127]
	v_pk_fma_f32 v[4:5], v[30:31], v[4:5], v[112:113]
	v_pk_add_f32 v[8:9], v[8:9], v[18:19]
	s_waitcnt vmcnt(0) lgkmcnt(0)
	v_mov_b64_e32 v[18:19], v[62:63]
	v_mov_b64_e32 v[22:23], v[46:47]
	v_mov_b64_e32 v[26:27], v[38:39]
	v_mov_b64_e32 v[30:31], v[34:35]
	v_pk_fma_f32 v[14:15], v[180:181], v[14:15], v[160:161]
	v_pk_add_f32 v[10:11], v[10:11], v[150:151]
	v_pk_fma_f32 v[2:3], v[54:55], v[2:3], v[128:129]
	s_add_i32 s4, s4, 8
	v_lshl_add_u64 v[90:91], v[90:91], 0, s[40:41]
	v_add_u32_e32 v88, 0x4000, v88
	s_mov_b32 s6, s5
	v_mov_b64_e32 v[20:21], v[64:65]
	v_mov_b64_e32 v[24:25], v[48:49]
	v_mov_b64_e32 v[28:29], v[40:41]
	v_mov_b64_e32 v[32:33], v[36:37]
	s_cbranch_vccnz .LBB0_1706
	ds_write_b128 v170, v[10:13]
	ds_write_b128 v170, v[6:9] offset:16
	ds_write_b128 v170, v[14:17] offset:16384
	ds_write_b128 v170, v[2:5] offset:16400
	v_or_b32_e32 v86, 0x1f800, v68
	v_mov_b32_e32 v87, v67
	v_lshl_add_u64 v[2:3], s[28:29], 0, v[70:71]
	s_mov_b32 s0, 0xf000
	v_or_b32_e32 v66, 0x1e800, v68
	v_lshl_add_u64 v[88:89], s[20:21], 0, v[86:87]
	v_add_co_u32_e32 v4, vcc, s0, v2
	v_or_b32_e32 v90, 0x1f000, v68
	v_mov_b32_e32 v91, v67
	v_lshl_add_u64 v[6:7], s[20:21], 0, v[66:67]
	v_or_b32_e32 v66, 0x1e000, v68
	v_addc_co_u32_e32 v5, vcc, 0, v3, vcc
	v_lshl_add_u64 v[92:93], s[20:21], 0, v[90:91]
	global_load_dwordx4 v[30:33], v[88:89], off
	global_load_dwordx4 v[26:29], v[92:93], off
	v_lshl_add_u64 v[8:9], s[20:21], 0, v[66:67]
	global_load_dwordx4 v[22:25], v[6:7], off
	global_load_dwordx4 v[18:21], v[8:9], off
	global_load_dwordx2 v[102:103], v[4:5], off offset:3072
	global_load_dwordx2 v[104:105], v[4:5], off offset:2048
	global_load_dwordx2 v[106:107], v[4:5], off offset:1024
	global_load_dwordx2 v[108:109], v[4:5], off
	s_mov_b64 s[0:1], 0xfc00
	v_lshl_add_u64 v[96:97], v[2:3], 0, s[0:1]
	s_mov_b64 s[0:1], 0xf800
	v_lshl_add_u64 v[94:95], v[2:3], 0, s[0:1]
	v_mov_b32_e32 v2, 0
	s_mov_b32 s6, 0
	v_lshl_add_u64 v[98:99], s[38:39], 0, v[72:73]
	v_add_u32_e32 v100, 0x1c000, v69
	s_mov_b32 s4, 8
	v_mov_b32_e32 v3, v2
	v_mov_b32_e32 v4, v2
	v_mov_b32_e32 v5, v2
	v_mov_b32_e32 v10, v2
	v_mov_b32_e32 v11, v2
	v_mov_b32_e32 v12, v2
	v_mov_b32_e32 v13, v2
	v_mov_b32_e32 v8, v2
	v_mov_b32_e32 v9, v2
	v_mov_b32_e32 v6, v2
	v_mov_b32_e32 v7, v2
	v_mov_b32_e32 v16, v2
	v_mov_b32_e32 v17, v2
	v_mov_b32_e32 v14, v2
	v_mov_b32_e32 v15, v2
.LBB0_1708:
	v_add_u32_e32 v66, 0x1800, v100
	v_lshl_add_u64 v[34:35], s[20:21], 0, v[66:67]
	v_add_u32_e32 v66, 0x1000, v100
	v_lshl_add_u64 v[36:37], s[20:21], 0, v[66:67]
	v_add_u32_e32 v66, 0x800, v100
	global_load_dwordx4 v[58:61], v[34:35], off nt
	global_load_dwordx4 v[54:57], v[36:37], off nt
	v_lshl_add_u64 v[34:35], s[20:21], 0, v[66:67]
	v_mov_b32_e32 v101, v67
	v_lshl_add_u64 v[36:37], s[20:21], 0, v[100:101]
	global_load_dwordx4 v[50:53], v[34:35], off nt
	global_load_dwordx4 v[42:45], v[36:37], off nt
	global_load_dwordx2 v[118:119], v[98:99], off offset:3072 nt
	global_load_dwordx2 v[120:121], v[98:99], off offset:2048 nt
	global_load_dwordx2 v[122:123], v[98:99], off offset:1024 nt
	global_load_dwordx2 v[124:125], v[98:99], off nt
	s_add_i32 s5, s6, 2
	s_cmp_lt_u32 s6, 14
	s_cselect_b64 s[0:1], -1, 0
	s_and_b64 vcc, s[0:1], exec
	s_cselect_b32 s0, s4, 60
	s_sub_i32 s1, 63, s0
	v_lshl_add_u32 v66, s1, 11, v68
	v_lshl_add_u64 v[34:35], s[20:21], 0, v[66:67]
	v_lshl_add_u32 v66, s1, 10, v70
	s_sub_i32 s1, 62, s0
	v_lshl_add_u64 v[38:39], s[28:29], 0, v[66:67]
	v_lshl_add_u32 v66, s1, 11, v68
	s_waitcnt vmcnt(0) lgkmcnt(0)
	v_cvt_pk_f32_fp8_e32 v[162:163], v102
	v_cvt_pk_f32_fp8_sdwa v[146:147], v102 src0_sel:WORD_1
	v_cvt_pk_f32_fp8_e32 v[130:131], v103
	v_cvt_pk_f32_fp8_sdwa v[114:115], v103 src0_sel:WORD_1
	global_load_dwordx2 v[102:103], v[38:39], off nt
	v_lshl_add_u64 v[38:39], s[20:21], 0, v[66:67]
	v_lshl_add_u32 v66, s1, 10, v70
	s_sub_i32 s1, 61, s0
	v_lshl_add_u64 v[46:47], s[28:29], 0, v[66:67]
	v_lshl_add_u32 v66, s1, 11, v68
	v_cvt_pk_f32_fp8_e32 v[164:165], v104
	v_cvt_pk_f32_fp8_sdwa v[148:149], v104 src0_sel:WORD_1
	v_cvt_pk_f32_fp8_e32 v[132:133], v105
	v_cvt_pk_f32_fp8_sdwa v[116:117], v105 src0_sel:WORD_1
	global_load_dwordx2 v[104:105], v[46:47], off nt
	v_lshl_add_u64 v[46:47], s[20:21], 0, v[66:67]
	v_lshl_add_u32 v66, s1, 10, v70
	s_sub_i32 s0, 60, s0
	v_lshl_add_u64 v[62:63], s[28:29], 0, v[66:67]
	v_lshl_add_u32 v66, s0, 11, v68
	v_cvt_pk_f32_fp8_e32 v[158:159], v106
	v_cvt_pk_f32_fp8_sdwa v[142:143], v106 src0_sel:WORD_1
	v_cvt_pk_f32_fp8_e32 v[126:127], v107
	v_cvt_pk_f32_fp8_sdwa v[110:111], v107 src0_sel:WORD_1
	global_load_dwordx2 v[106:107], v[62:63], off nt
	v_lshl_add_u64 v[62:63], s[20:21], 0, v[66:67]
	v_lshl_add_u32 v66, s0, 10, v70
	v_cvt_pk_f32_fp8_e32 v[160:161], v108
	v_cvt_pk_f32_fp8_sdwa v[144:145], v108 src0_sel:WORD_1
	v_cvt_pk_f32_fp8_e32 v[128:129], v109
	v_cvt_pk_f32_fp8_sdwa v[112:113], v109 src0_sel:WORD_1
	v_lshl_add_u64 v[108:109], s[28:29], 0, v[66:67]
	global_load_dwordx2 v[108:109], v[108:109], off nt
	s_nop 0
	global_load_dwordx4 v[34:37], v[34:35], off nt
	s_nop 0
	global_load_dwordx4 v[38:41], v[38:39], off nt
	s_nop 0
	global_load_dwordx4 v[46:49], v[46:47], off nt
	s_nop 0
	global_load_dwordx4 v[62:65], v[62:63], off nt
	v_lshlrev_b32_e32 v184, 16, v30
	v_and_b32_e32 v185, 0xffff0000, v30
	v_mul_f32_e32 v30, 0x3fb8aa3b, v184
	v_exp_f32_e32 v186, v30
	v_mul_f32_e32 v30, 0x3fb8aa3b, v185
	v_pk_add_f32 v[2:3], v[2:3], v[184:185]
	v_lshlrev_b32_e32 v184, 16, v26
	v_exp_f32_e32 v187, v30
	v_and_b32_e32 v185, 0xffff0000, v26
	v_mul_f32_e32 v26, 0x3fb8aa3b, v184
	v_exp_f32_e32 v188, v26
	v_mul_f32_e32 v26, 0x3fb8aa3b, v185
	v_exp_f32_e32 v189, v26
	v_pk_add_f32 v[2:3], v[2:3], v[184:185]
	v_lshlrev_b32_e32 v184, 16, v22
	v_and_b32_e32 v185, 0xffff0000, v22
	v_pk_fma_f32 v[14:15], v[14:15], v[186:187], v[162:163]
	v_lshlrev_b32_e32 v162, 16, v18
	v_pk_add_f32 v[2:3], v[2:3], v[184:185]
	v_and_b32_e32 v163, 0xffff0000, v18
	v_mul_f32_e32 v18, 0x3fb8aa3b, v162
	v_pk_fma_f32 v[14:15], v[188:189], v[14:15], v[164:165]
	v_exp_f32_e32 v164, v18
	v_mul_f32_e32 v18, 0x3fb8aa3b, v163
	v_pk_add_f32 v[2:3], v[2:3], v[162:163]
	v_lshlrev_b32_e32 v162, 16, v58
	v_exp_f32_e32 v165, v18
	v_and_b32_e32 v163, 0xffff0000, v58
	v_mul_f32_e32 v18, 0x3fb8aa3b, v162
	v_mul_f32_e32 v22, 0x3fb8aa3b, v184
	v_exp_f32_e32 v184, v18
	v_mul_f32_e32 v18, 0x3fb8aa3b, v163
	v_pk_add_f32 v[2:3], v[2:3], v[162:163]
	v_lshlrev_b32_e32 v162, 16, v54
	v_exp_f32_e32 v190, v22
	v_mul_f32_e32 v22, 0x3fb8aa3b, v185
	v_exp_f32_e32 v185, v18
	v_and_b32_e32 v163, 0xffff0000, v54
	v_mul_f32_e32 v18, 0x3fb8aa3b, v162
	v_exp_f32_e32 v186, v18
	v_mul_f32_e32 v18, 0x3fb8aa3b, v163
	v_pk_add_f32 v[2:3], v[2:3], v[162:163]
	v_lshlrev_b32_e32 v162, 16, v50
	v_exp_f32_e32 v187, v18
	v_and_b32_e32 v163, 0xffff0000, v50
	v_mul_f32_e32 v18, 0x3fb8aa3b, v162
	v_exp_f32_e32 v191, v22
	v_exp_f32_e32 v188, v18
	v_mul_f32_e32 v18, 0x3fb8aa3b, v163
	v_pk_add_f32 v[2:3], v[2:3], v[162:163]
	v_lshlrev_b32_e32 v162, 16, v42
	v_exp_f32_e32 v189, v18
	v_and_b32_e32 v163, 0xffff0000, v42
	v_mul_f32_e32 v18, 0x3fb8aa3b, v162
	v_exp_f32_e32 v192, v18
	v_mul_f32_e32 v18, 0x3fb8aa3b, v163
	v_lshlrev_b32_e32 v30, 16, v31
	v_exp_f32_e32 v193, v18
	v_and_b32_e32 v31, 0xffff0000, v31
	v_mul_f32_e32 v18, 0x3fb8aa3b, v30
	v_pk_fma_f32 v[14:15], v[190:191], v[14:15], v[158:159]
	v_exp_f32_e32 v158, v18
	v_mul_f32_e32 v18, 0x3fb8aa3b, v31
	v_lshlrev_b32_e32 v26, 16, v27
	v_exp_f32_e32 v159, v18
	v_and_b32_e32 v27, 0xffff0000, v27
	v_mul_f32_e32 v18, 0x3fb8aa3b, v26
	v_pk_add_f32 v[4:5], v[4:5], v[30:31]
	v_exp_f32_e32 v30, v18
	v_mul_f32_e32 v18, 0x3fb8aa3b, v27
	v_lshlrev_b32_e32 v22, 16, v23
	v_exp_f32_e32 v31, v18
	v_and_b32_e32 v23, 0xffff0000, v23
	v_mul_f32_e32 v18, 0x3fb8aa3b, v22
	v_pk_add_f32 v[4:5], v[4:5], v[26:27]
	v_exp_f32_e32 v26, v18
	v_mul_f32_e32 v18, 0x3fb8aa3b, v23
	v_exp_f32_e32 v27, v18
	v_pk_add_f32 v[4:5], v[4:5], v[22:23]
	v_lshlrev_b32_e32 v18, 16, v19
	v_and_b32_e32 v19, 0xffff0000, v19
	v_pk_fma_f32 v[16:17], v[16:17], v[158:159], v[146:147]
	v_mul_f32_e32 v22, 0x3fb8aa3b, v18
	v_mul_f32_e32 v23, 0x3fb8aa3b, v19
	v_pk_add_f32 v[4:5], v[4:5], v[18:19]
	v_lshlrev_b32_e32 v18, 16, v59
	v_and_b32_e32 v19, 0xffff0000, v59
	v_pk_fma_f32 v[16:17], v[30:31], v[16:17], v[148:149]
	v_mul_f32_e32 v30, 0x3fb8aa3b, v18
	v_pk_add_f32 v[4:5], v[4:5], v[18:19]
	v_lshlrev_b32_e32 v18, 16, v55
	v_mul_f32_e32 v31, 0x3fb8aa3b, v19
	v_and_b32_e32 v19, 0xffff0000, v55
	v_mul_f32_e32 v42, 0x3fb8aa3b, v18
	v_exp_f32_e32 v22, v22
	v_exp_f32_e32 v23, v23
	v_exp_f32_e32 v54, v42
	v_mul_f32_e32 v42, 0x3fb8aa3b, v19
	v_pk_add_f32 v[4:5], v[4:5], v[18:19]
	v_lshlrev_b32_e32 v18, 16, v51
	v_exp_f32_e32 v55, v42
	v_and_b32_e32 v19, 0xffff0000, v51
	v_mul_f32_e32 v42, 0x3fb8aa3b, v18
	v_exp_f32_e32 v50, v42
	v_mul_f32_e32 v42, 0x3fb8aa3b, v19
	v_pk_add_f32 v[4:5], v[4:5], v[18:19]
	v_lshlrev_b32_e32 v18, 16, v43
	v_and_b32_e32 v19, 0xffff0000, v43
	v_exp_f32_e32 v51, v42
	v_mul_f32_e32 v42, 0x3fb8aa3b, v18
	v_mul_f32_e32 v43, 0x3fb8aa3b, v19
	v_pk_fma_f32 v[16:17], v[26:27], v[16:17], v[142:143]
	v_pk_add_f32 v[4:5], v[4:5], v[18:19]
	v_lshlrev_b32_e32 v18, 16, v32
	v_and_b32_e32 v19, 0xffff0000, v32
	v_cvt_pk_f32_fp8_sdwa v[150:151], v118 src0_sel:WORD_1
	v_exp_f32_e32 v30, v30
	v_exp_f32_e32 v31, v31
	v_pk_fma_f32 v[16:17], v[22:23], v[16:17], v[144:145]
	v_mul_f32_e32 v22, 0x3fb8aa3b, v18
	v_mul_f32_e32 v23, 0x3fb8aa3b, v19
	v_exp_f32_e32 v22, v22
	v_exp_f32_e32 v23, v23
	v_pk_add_f32 v[10:11], v[10:11], v[18:19]
	v_lshlrev_b32_e32 v18, 16, v28
	v_and_b32_e32 v19, 0xffff0000, v28
	v_mul_f32_e32 v26, 0x3fb8aa3b, v18
	v_mul_f32_e32 v27, 0x3fb8aa3b, v19
	v_pk_add_f32 v[10:11], v[10:11], v[18:19]
	v_lshlrev_b32_e32 v18, 16, v24
	v_and_b32_e32 v19, 0xffff0000, v24
	v_cvt_pk_f32_fp8_sdwa v[152:153], v120 src0_sel:WORD_1
	v_exp_f32_e32 v26, v26
	v_exp_f32_e32 v27, v27
	v_mul_f32_e32 v24, 0x3fb8aa3b, v18
	v_pk_add_f32 v[10:11], v[10:11], v[18:19]
	v_lshlrev_b32_e32 v18, 16, v20
	v_cvt_pk_f32_fp8_sdwa v[154:155], v122 src0_sel:WORD_1
	v_pk_fma_f32 v[16:17], v[30:31], v[16:17], v[150:151]
	v_exp_f32_e32 v30, v24
	v_mul_f32_e32 v24, 0x3fb8aa3b, v19
	v_and_b32_e32 v19, 0xffff0000, v20
	v_mul_f32_e32 v20, 0x3fb8aa3b, v18
	v_cvt_pk_f32_fp8_sdwa v[156:157], v124 src0_sel:WORD_1
	v_exp_f32_e32 v42, v42
	v_exp_f32_e32 v43, v43
	v_pk_fma_f32 v[6:7], v[6:7], v[22:23], v[130:131]
	v_exp_f32_e32 v22, v20
	v_mul_f32_e32 v20, 0x3fb8aa3b, v19
	v_pk_add_f32 v[10:11], v[10:11], v[18:19]
	v_lshlrev_b32_e32 v18, 16, v60
	v_exp_f32_e32 v23, v20
	v_and_b32_e32 v19, 0xffff0000, v60
	v_mul_f32_e32 v20, 0x3fb8aa3b, v18
	v_pk_fma_f32 v[16:17], v[54:55], v[16:17], v[152:153]
	v_pk_fma_f32 v[6:7], v[26:27], v[6:7], v[132:133]
	v_exp_f32_e32 v26, v20
	v_mul_f32_e32 v20, 0x3fb8aa3b, v19
	v_pk_add_f32 v[10:11], v[10:11], v[18:19]
	v_lshlrev_b32_e32 v18, 16, v56
	v_pk_fma_f32 v[16:17], v[50:51], v[16:17], v[154:155]
	v_exp_f32_e32 v27, v20
	v_and_b32_e32 v19, 0xffff0000, v56
	v_mul_f32_e32 v20, 0x3fb8aa3b, v18
	v_pk_fma_f32 v[16:17], v[42:43], v[16:17], v[156:157]
	v_exp_f32_e32 v42, v20
	v_mul_f32_e32 v20, 0x3fb8aa3b, v19
	v_pk_add_f32 v[10:11], v[10:11], v[18:19]
	v_lshlrev_b32_e32 v18, 16, v52
	v_exp_f32_e32 v31, v24
	v_exp_f32_e32 v43, v20
	v_and_b32_e32 v19, 0xffff0000, v52
	v_mul_f32_e32 v20, 0x3fb8aa3b, v18
	v_exp_f32_e32 v50, v20
	v_mul_f32_e32 v20, 0x3fb8aa3b, v19
	v_pk_add_f32 v[10:11], v[10:11], v[18:19]
	v_lshlrev_b32_e32 v18, 16, v44
	v_exp_f32_e32 v51, v20
	v_and_b32_e32 v19, 0xffff0000, v44
	v_mul_f32_e32 v20, 0x3fb8aa3b, v18
	v_cvt_pk_f32_fp8_e32 v[134:135], v119
	v_exp_f32_e32 v54, v20
	v_mul_f32_e32 v20, 0x3fb8aa3b, v19
	v_pk_add_f32 v[10:11], v[10:11], v[18:19]
	v_lshlrev_b32_e32 v18, 16, v33
	v_exp_f32_e32 v55, v20
	v_pk_fma_f32 v[6:7], v[30:31], v[6:7], v[126:127]
	v_and_b32_e32 v19, 0xffff0000, v33
	v_mul_f32_e32 v20, 0x3fb8aa3b, v18
	v_pk_fma_f32 v[6:7], v[22:23], v[6:7], v[128:129]
	v_exp_f32_e32 v22, v20
	v_mul_f32_e32 v20, 0x3fb8aa3b, v19
	v_pk_add_f32 v[12:13], v[12:13], v[18:19]
	v_lshlrev_b32_e32 v18, 16, v29
	v_exp_f32_e32 v23, v20
	v_and_b32_e32 v19, 0xffff0000, v29
	v_mul_f32_e32 v20, 0x3fb8aa3b, v18
	v_pk_fma_f32 v[6:7], v[26:27], v[6:7], v[134:135]
	v_exp_f32_e32 v26, v20
	v_mul_f32_e32 v20, 0x3fb8aa3b, v19
	v_pk_add_f32 v[12:13], v[12:13], v[18:19]
	v_lshlrev_b32_e32 v18, 16, v25
	v_exp_f32_e32 v27, v20
	v_and_b32_e32 v19, 0xffff0000, v25
	v_mul_f32_e32 v20, 0x3fb8aa3b, v18
	v_exp_f32_e32 v24, v20
	v_mul_f32_e32 v20, 0x3fb8aa3b, v19
	v_pk_add_f32 v[12:13], v[12:13], v[18:19]
	v_lshlrev_b32_e32 v18, 16, v21
	v_and_b32_e32 v19, 0xffff0000, v21
	v_exp_f32_e32 v25, v20
	v_mul_f32_e32 v20, 0x3fb8aa3b, v18
	v_mul_f32_e32 v21, 0x3fb8aa3b, v19
	v_pk_add_f32 v[12:13], v[12:13], v[18:19]
	v_lshlrev_b32_e32 v18, 16, v61
	v_and_b32_e32 v19, 0xffff0000, v61
	v_pk_fma_f32 v[8:9], v[8:9], v[22:23], v[114:115]
	v_exp_f32_e32 v20, v20
	v_exp_f32_e32 v21, v21
	v_mul_f32_e32 v22, 0x3fb8aa3b, v18
	v_mul_f32_e32 v23, 0x3fb8aa3b, v19
	v_pk_add_f32 v[12:13], v[12:13], v[18:19]
	v_lshlrev_b32_e32 v18, 16, v57
	v_and_b32_e32 v19, 0xffff0000, v57
	v_cvt_pk_f32_fp8_e32 v[176:177], v118
	v_cvt_pk_f32_fp8_sdwa v[118:119], v119 src0_sel:WORD_1
	v_pk_fma_f32 v[8:9], v[26:27], v[8:9], v[116:117]
	v_exp_f32_e32 v22, v22
	v_exp_f32_e32 v23, v23
	v_mul_f32_e32 v26, 0x3fb8aa3b, v18
	v_mul_f32_e32 v27, 0x3fb8aa3b, v19
	v_pk_add_f32 v[12:13], v[12:13], v[18:19]
	v_lshlrev_b32_e32 v18, 16, v53
	v_and_b32_e32 v19, 0xffff0000, v53
	v_cvt_pk_f32_fp8_e32 v[178:179], v120
	v_cvt_pk_f32_fp8_e32 v[136:137], v121
	v_cvt_pk_f32_fp8_sdwa v[120:121], v121 src0_sel:WORD_1
	v_exp_f32_e32 v26, v26
	v_exp_f32_e32 v27, v27
	v_mul_f32_e32 v28, 0x3fb8aa3b, v18
	v_mul_f32_e32 v29, 0x3fb8aa3b, v19
	v_pk_add_f32 v[12:13], v[12:13], v[18:19]
	v_lshlrev_b32_e32 v18, 16, v45
	v_and_b32_e32 v19, 0xffff0000, v45
	v_cvt_pk_f32_fp8_e32 v[180:181], v122
	v_cvt_pk_f32_fp8_e32 v[138:139], v123
	v_cvt_pk_f32_fp8_sdwa v[122:123], v123 src0_sel:WORD_1
	v_exp_f32_e32 v28, v28
	v_exp_f32_e32 v29, v29
	v_mul_f32_e32 v30, 0x3fb8aa3b, v18
	v_mul_f32_e32 v31, 0x3fb8aa3b, v19
	v_pk_fma_f32 v[8:9], v[24:25], v[8:9], v[110:111]
	v_cvt_pk_f32_fp8_e32 v[182:183], v124
	v_cvt_pk_f32_fp8_e32 v[140:141], v125
	v_cvt_pk_f32_fp8_sdwa v[124:125], v125 src0_sel:WORD_1
	v_exp_f32_e32 v30, v30
	v_exp_f32_e32 v31, v31
	v_pk_fma_f32 v[8:9], v[20:21], v[8:9], v[112:113]
	v_pk_fma_f32 v[14:15], v[164:165], v[14:15], v[160:161]
	v_pk_fma_f32 v[8:9], v[22:23], v[8:9], v[118:119]
	v_pk_fma_f32 v[14:15], v[184:185], v[14:15], v[176:177]
	v_pk_fma_f32 v[8:9], v[26:27], v[8:9], v[120:121]
	v_pk_fma_f32 v[14:15], v[186:187], v[14:15], v[178:179]
	v_pk_fma_f32 v[6:7], v[42:43], v[6:7], v[136:137]
	v_pk_fma_f32 v[8:9], v[28:29], v[8:9], v[122:123]
	s_movk_i32 s0, 0xe000
	v_pk_fma_f32 v[14:15], v[188:189], v[14:15], v[180:181]
	v_pk_fma_f32 v[6:7], v[50:51], v[6:7], v[138:139]
	v_pk_fma_f32 v[8:9], v[30:31], v[8:9], v[124:125]
	v_pk_add_f32 v[12:13], v[12:13], v[18:19]
	s_mov_b32 s1, -1
	s_waitcnt vmcnt(0) lgkmcnt(0)
	v_mov_b64_e32 v[18:19], v[62:63]
	v_mov_b64_e32 v[22:23], v[46:47]
	v_mov_b64_e32 v[26:27], v[38:39]
	v_mov_b64_e32 v[30:31], v[34:35]
	v_pk_fma_f32 v[14:15], v[192:193], v[14:15], v[182:183]
	v_pk_add_f32 v[2:3], v[2:3], v[162:163]
	v_pk_fma_f32 v[6:7], v[54:55], v[6:7], v[140:141]
	s_add_i32 s4, s4, 8
	v_lshl_add_u64 v[98:99], v[98:99], 0, s[0:1]
	v_add_u32_e32 v100, 0xffffc000, v100
	s_mov_b32 s6, s5
	v_mov_b64_e32 v[20:21], v[64:65]
	v_mov_b64_e32 v[24:25], v[48:49]
	v_mov_b64_e32 v[28:29], v[40:41]
	v_mov_b64_e32 v[32:33], v[36:37]
	s_cbranch_vccnz .LBB0_1708
	v_mov_b32_e32 v35, 0
	v_mov_b32_e32 v34, v35
	v_mov_b32_e32 v37, v35
	v_mov_b32_e32 v36, v35
	v_mov_b32_e32 v39, v35
	v_mov_b32_e32 v38, v35
	v_mov_b32_e32 v41, v35
	v_mov_b32_e32 v40, v35
	ds_write_b128 v170, v[2:5] offset:32768
	ds_write_b128 v170, v[10:13] offset:32784
	ds_write_b128 v170, v[14:17] offset:49152
	ds_write_b128 v170, v[6:9] offset:49168
	s_waitcnt lgkmcnt(0)
	s_barrier
	s_and_saveexec_b64 s[44:45], s[34:35]
	s_cbranch_execz .LBB0_1719
	v_mov_b32_e32 v66, v67
	v_mov_b32_e32 v2, 0
	v_mov_b64_e32 v[34:35], v[66:67]
	v_mov_b64_e32 v[36:37], v[66:67]
	v_mov_b64_e32 v[38:39], v[66:67]
	v_mov_b64_e32 v[40:41], v[66:67]
	s_and_saveexec_b64 s[46:47], s[14:15]
	s_cbranch_execz .LBB0_1714
	v_mov_b32_e32 v40, 0
	s_mov_b32 s4, 0
	v_mov_b32_e32 v2, v171
	v_mov_b32_e32 v41, v40
	v_mov_b32_e32 v38, v40
	v_mov_b32_e32 v39, v40
	v_mov_b32_e32 v36, v40
	v_mov_b32_e32 v37, v40
	v_mov_b32_e32 v34, v40
	v_mov_b32_e32 v35, v40

.LBB0_1724:
	v_add_u32_e32 v66, 0x2000, v42
	v_add_u32_e32 v76, 0x2800, v42
	v_mov_b32_e32 v77, v67
	v_lshl_add_u64 v[2:3], s[18:19], 0, v[66:67]
	v_lshl_add_u64 v[4:5], s[18:19], 0, v[76:77]
	v_add_u32_e32 v54, 0x3000, v42
	v_mov_b32_e32 v55, v67
	v_add_u32_e32 v44, 0x3800, v42
	v_mov_b32_e32 v45, v67
	global_load_dwordx4 v[30:33], v[2:3], off nt
	global_load_dwordx4 v[26:29], v[4:5], off nt
	v_lshl_add_u64 v[2:3], s[18:19], 0, v[54:55]
	v_lshl_add_u64 v[4:5], s[18:19], 0, v[44:45]
	global_load_dwordx4 v[6:9], v[2:3], off nt
	s_nop 0
	global_load_dwordx4 v[2:5], v[4:5], off nt
	s_nop 0
	global_load_dwordx2 v[82:83], v[74:75], off nt
	global_load_dwordx2 v[80:81], v[74:75], off offset:1024 nt
	global_load_dwordx2 v[58:59], v[74:75], off offset:2048 nt
	global_load_dwordx2 v[56:57], v[74:75], off offset:3072 nt
	s_waitcnt vmcnt(0) lgkmcnt(0)
	v_lshlrev_b32_e32 v43, 16, v22
	v_and_b32_e32 v22, 0xffff0000, v22
	v_mul_f32_e32 v43, 0x3fb8aa3b, v43
	v_mul_f32_e32 v22, 0x3fb8aa3b, v22
	v_cvt_pk_f32_fp8_e32 v[84:85], v78
	v_exp_f32_e32 v102, v43
	v_exp_f32_e32 v103, v22
	v_lshlrev_b32_e32 v22, 16, v23
	v_and_b32_e32 v23, 0xffff0000, v23
	v_mul_f32_e32 v22, 0x3fb8aa3b, v22
	v_exp_f32_e32 v104, v22
	v_mul_f32_e32 v22, 0x3fb8aa3b, v23
	v_lshlrev_b32_e32 v23, 16, v24
	v_cvt_pk_f32_fp8_sdwa v[98:99], v78 src0_sel:WORD_1
	v_exp_f32_e32 v105, v22
	v_and_b32_e32 v24, 0xffff0000, v24
	v_mul_f32_e32 v23, 0x3fb8aa3b, v23
	v_pk_fma_f32 v[34:35], v[34:35], v[102:103], v[84:85]
	v_exp_f32_e32 v84, v23
	v_mul_f32_e32 v23, 0x3fb8aa3b, v24
	v_exp_f32_e32 v85, v23
	v_lshlrev_b32_e32 v23, 16, v25
	v_and_b32_e32 v24, 0xffff0000, v25
	v_mul_f32_e32 v23, 0x3fb8aa3b, v23
	v_pk_fma_f32 v[36:37], v[36:37], v[104:105], v[98:99]
	v_exp_f32_e32 v98, v23
	v_mul_f32_e32 v23, 0x3fb8aa3b, v24
	v_cvt_pk_f32_fp8_e32 v[100:101], v79
	v_cvt_pk_f32_fp8_sdwa v[78:79], v79 src0_sel:WORD_1
	v_exp_f32_e32 v99, v23
	v_mov_b32_e32 v43, v67
	v_pk_fma_f32 v[38:39], v[38:39], v[84:85], v[100:101]
	v_cvt_pk_bf16_f32 v22, v34, v35
	v_pk_fma_f32 v[40:41], v[40:41], v[98:99], v[78:79]
	v_lshl_add_u64 v[78:79], s[30:31], 0, v[42:43]
	v_lshlrev_b32_e32 v43, 16, v18
	v_and_b32_e32 v18, 0xffff0000, v18
	v_mul_f32_e32 v18, 0x3fb8aa3b, v18
	v_exp_f32_e32 v85, v18
	v_lshlrev_b32_e32 v18, 16, v19
	v_and_b32_e32 v19, 0xffff0000, v19
	v_cvt_pk_bf16_f32 v23, v36, v37
	v_cvt_pk_bf16_f32 v24, v38, v39
	v_cvt_pk_bf16_f32 v25, v40, v41
	v_mul_f32_e32 v18, 0x3fb8aa3b, v18
	v_mul_f32_e32 v19, 0x3fb8aa3b, v19
	global_store_dwordx4 v[78:79], v[22:25], off
	v_exp_f32_e32 v18, v18
	v_exp_f32_e32 v19, v19
	v_cvt_pk_f32_fp8_sdwa v[24:25], v64 src0_sel:WORD_1
	v_mul_f32_e32 v43, 0x3fb8aa3b, v43
	v_cvt_pk_f32_fp8_e32 v[22:23], v64
	v_cvt_pk_f32_fp8_e32 v[78:79], v65
	v_pk_fma_f32 v[24:25], v[18:19], v[36:37], v[24:25]
	v_lshlrev_b32_e32 v18, 16, v20
	v_and_b32_e32 v19, 0xffff0000, v20
	v_lshlrev_b32_e32 v20, 16, v21
	v_and_b32_e32 v21, 0xffff0000, v21
	v_mul_f32_e32 v18, 0x3fb8aa3b, v18
	v_mul_f32_e32 v19, 0x3fb8aa3b, v19
	v_mul_f32_e32 v20, 0x3fb8aa3b, v20
	v_mul_f32_e32 v21, 0x3fb8aa3b, v21
	v_exp_f32_e32 v84, v43
	v_cvt_pk_f32_fp8_sdwa v[98:99], v65 src0_sel:WORD_1
	v_exp_f32_e32 v18, v18
	v_exp_f32_e32 v19, v19
	v_exp_f32_e32 v20, v20
	v_exp_f32_e32 v21, v21
	v_pk_fma_f32 v[64:65], v[84:85], v[34:35], v[22:23]
	v_pk_fma_f32 v[22:23], v[18:19], v[38:39], v[78:79]
	v_cvt_pk_bf16_f32 v34, v64, v65
	v_pk_fma_f32 v[18:19], v[20:21], v[40:41], v[98:99]
	v_add_u32_e32 v20, 0x800, v42
	v_mov_b32_e32 v21, v67
	v_cvt_pk_bf16_f32 v35, v24, v25
	v_cvt_pk_bf16_f32 v36, v22, v23
	v_cvt_pk_bf16_f32 v37, v18, v19
	v_lshl_add_u64 v[20:21], s[30:31], 0, v[20:21]
	global_store_dwordx4 v[20:21], v[34:37], off
	v_lshlrev_b32_e32 v38, 16, v10
	v_and_b32_e32 v10, 0xffff0000, v10
	v_lshlrev_b32_e32 v36, 16, v14
	v_mul_f32_e32 v36, 0x3fb8aa3b, v36
	v_mul_f32_e32 v10, 0x3fb8aa3b, v10
	v_exp_f32_e32 v106, v36
	v_cvt_pk_f32_fp8_e32 v[114:115], v61
	v_cvt_pk_f32_fp8_sdwa v[36:37], v61 src0_sel:WORD_1
	v_exp_f32_e32 v61, v10
	v_lshlrev_b32_e32 v10, 16, v11
	v_and_b32_e32 v11, 0xffff0000, v11
	v_mul_f32_e32 v10, 0x3fb8aa3b, v10
	v_exp_f32_e32 v116, v10
	v_mul_f32_e32 v10, 0x3fb8aa3b, v11
	v_exp_f32_e32 v117, v10
	v_lshlrev_b32_e32 v10, 16, v12
	v_and_b32_e32 v11, 0xffff0000, v12
	v_mul_f32_e32 v10, 0x3fb8aa3b, v10
	v_exp_f32_e32 v118, v10
	v_mul_f32_e32 v10, 0x3fb8aa3b, v11
	v_exp_f32_e32 v119, v10
	v_lshlrev_b32_e32 v10, 16, v13
	v_and_b32_e32 v11, 0xffff0000, v13
	v_mul_f32_e32 v10, 0x3fb8aa3b, v10
	s_add_i32 s4, s5, 2
	v_exp_f32_e32 v120, v10
	v_mul_f32_e32 v10, 0x3fb8aa3b, v11
	s_cmp_lt_u32 s5, 14
	v_exp_f32_e32 v121, v10
	v_add_u32_e32 v10, 0x1800, v42
	v_mov_b32_e32 v11, v67
	s_cselect_b32 s0, s4, 15
	v_lshl_add_u64 v[122:123], s[30:31], 0, v[10:11]
	s_lshl_b32 s1, s0, 2
	v_lshl_add_u32 v10, s0, 13, v68
	s_or_b32 s6, s1, 1
	v_lshl_add_u64 v[124:125], s[18:19], 0, v[10:11]
	v_lshl_add_u32 v10, s0, 12, v70
	v_lshl_add_u64 v[126:127], s[24:25], 0, v[10:11]
	v_lshl_add_u32 v10, s6, 11, v68
	s_or_b32 s7, s1, 2
	v_lshl_add_u64 v[128:129], s[18:19], 0, v[10:11]
	v_lshl_add_u32 v10, s6, 10, v70
	v_lshl_add_u64 v[130:131], s[24:25], 0, v[10:11]
	v_lshl_add_u32 v10, s7, 11, v68
	s_or_b32 s1, s1, 3
	v_lshl_add_u64 v[132:133], s[18:19], 0, v[10:11]
	v_lshl_add_u32 v10, s7, 10, v70
	v_lshl_add_u64 v[134:135], s[24:25], 0, v[10:11]
	v_lshl_add_u32 v10, s1, 11, v68
	v_lshl_add_u64 v[136:137], s[18:19], 0, v[10:11]
	v_lshl_add_u32 v10, s1, 10, v70
	v_lshl_add_u64 v[138:139], s[24:25], 0, v[10:11]
	v_lshlrev_b32_e32 v10, 16, v30
	v_and_b32_e32 v11, 0xffff0000, v30
	v_mul_f32_e32 v10, 0x3fb8aa3b, v10
	v_exp_f32_e32 v140, v10
	v_mul_f32_e32 v10, 0x3fb8aa3b, v11
	v_exp_f32_e32 v141, v10
	v_lshlrev_b32_e32 v10, 16, v31
	v_and_b32_e32 v11, 0xffff0000, v31
	v_mul_f32_e32 v10, 0x3fb8aa3b, v10
	v_exp_f32_e32 v102, v10
	v_mul_f32_e32 v10, 0x3fb8aa3b, v11
	v_exp_f32_e32 v103, v10
	v_lshlrev_b32_e32 v10, 16, v32
	v_and_b32_e32 v11, 0xffff0000, v32
	v_mul_f32_e32 v10, 0x3fb8aa3b, v10
	v_exp_f32_e32 v98, v10
	v_mul_f32_e32 v10, 0x3fb8aa3b, v11
	v_exp_f32_e32 v99, v10
	v_lshlrev_b32_e32 v10, 16, v33
	v_and_b32_e32 v14, 0xffff0000, v14
	v_and_b32_e32 v11, 0xffff0000, v33
	v_mul_f32_e32 v10, 0x3fb8aa3b, v10
	v_mul_f32_e32 v14, 0x3fb8aa3b, v14
	v_mul_f32_e32 v38, 0x3fb8aa3b, v38
	v_cvt_pk_f32_fp8_e32 v[100:101], v82
	v_cvt_pk_f32_fp8_sdwa v[84:85], v82 src0_sel:WORD_1
	v_exp_f32_e32 v82, v10
	v_mul_f32_e32 v10, 0x3fb8aa3b, v11
	v_exp_f32_e32 v107, v14
	v_lshlrev_b32_e32 v14, 16, v15
	v_cvt_pk_f32_fp8_e32 v[110:111], v60
	v_cvt_pk_f32_fp8_sdwa v[112:113], v60 src0_sel:WORD_1
	v_exp_f32_e32 v60, v38
	v_cvt_pk_f32_fp8_e32 v[38:39], v83
	v_cvt_pk_f32_fp8_sdwa v[40:41], v83 src0_sel:WORD_1
	v_exp_f32_e32 v83, v10
	v_lshlrev_b32_e32 v10, 16, v26
	v_and_b32_e32 v15, 0xffff0000, v15
	v_mul_f32_e32 v14, 0x3fb8aa3b, v14
	v_and_b32_e32 v11, 0xffff0000, v26
	v_mul_f32_e32 v10, 0x3fb8aa3b, v10
	v_exp_f32_e32 v108, v14
	v_mul_f32_e32 v14, 0x3fb8aa3b, v15
	v_cvt_pk_f32_fp8_e32 v[142:143], v80
	v_cvt_pk_f32_fp8_sdwa v[144:145], v80 src0_sel:WORD_1
	v_exp_f32_e32 v80, v10
	v_mul_f32_e32 v10, 0x3fb8aa3b, v11
	v_exp_f32_e32 v109, v14
	v_lshlrev_b32_e32 v14, 16, v16
	v_cvt_pk_f32_fp8_e32 v[146:147], v81
	v_cvt_pk_f32_fp8_sdwa v[32:33], v81 src0_sel:WORD_1
	v_exp_f32_e32 v81, v10
	v_lshlrev_b32_e32 v10, 16, v27
	v_and_b32_e32 v15, 0xffff0000, v16
	v_mul_f32_e32 v14, 0x3fb8aa3b, v14
	v_and_b32_e32 v11, 0xffff0000, v27
	v_mul_f32_e32 v10, 0x3fb8aa3b, v10
	v_cvt_pk_f32_fp8_e32 v[78:79], v62
	v_cvt_pk_f32_fp8_sdwa v[104:105], v62 src0_sel:WORD_1
	v_exp_f32_e32 v62, v14
	v_mul_f32_e32 v14, 0x3fb8aa3b, v15
	v_exp_f32_e32 v148, v10
	v_mul_f32_e32 v10, 0x3fb8aa3b, v11
	v_cvt_pk_f32_fp8_e32 v[34:35], v63
	v_cvt_pk_f32_fp8_sdwa v[20:21], v63 src0_sel:WORD_1
	v_exp_f32_e32 v63, v14
	v_lshlrev_b32_e32 v14, 16, v17
	v_and_b32_e32 v15, 0xffff0000, v17
	v_exp_f32_e32 v149, v10
	v_lshlrev_b32_e32 v10, 16, v28
	v_mul_f32_e32 v14, 0x3fb8aa3b, v14
	v_mul_f32_e32 v15, 0x3fb8aa3b, v15
	v_and_b32_e32 v11, 0xffff0000, v28
	v_mul_f32_e32 v10, 0x3fb8aa3b, v10
	v_exp_f32_e32 v14, v14
	v_exp_f32_e32 v15, v15
	v_exp_f32_e32 v150, v10
	v_mul_f32_e32 v10, 0x3fb8aa3b, v11
	v_exp_f32_e32 v151, v10
	v_lshlrev_b32_e32 v10, 16, v29
	v_and_b32_e32 v11, 0xffff0000, v29
	v_mul_f32_e32 v10, 0x3fb8aa3b, v10
	v_exp_f32_e32 v28, v10
	v_mul_f32_e32 v10, 0x3fb8aa3b, v11
	v_pk_fma_f32 v[12:13], v[106:107], v[64:65], v[78:79]
	v_exp_f32_e32 v29, v10
	v_cvt_pk_bf16_f32 v10, v12, v13
	v_pk_fma_f32 v[106:107], v[60:61], v[12:13], v[110:111]
	v_pk_fma_f32 v[12:13], v[108:109], v[24:25], v[104:105]
	v_pk_fma_f32 v[22:23], v[62:63], v[22:23], v[34:35]
	v_pk_fma_f32 v[14:15], v[14:15], v[18:19], v[20:21]
	v_add_u32_e32 v16, 0x1000, v42
	v_mov_b32_e32 v17, v67
	v_pk_fma_f32 v[104:105], v[116:117], v[12:13], v[112:113]
	v_pk_fma_f32 v[108:109], v[118:119], v[22:23], v[114:115]
	v_pk_fma_f32 v[110:111], v[120:121], v[14:15], v[36:37]
	v_lshl_add_u64 v[16:17], s[30:31], 0, v[16:17]
	v_cvt_pk_bf16_f32 v60, v106, v107
	v_cvt_pk_bf16_f32 v11, v12, v13
	v_cvt_pk_bf16_f32 v61, v104, v105
	v_cvt_pk_bf16_f32 v12, v22, v23
	v_cvt_pk_bf16_f32 v62, v108, v109
	v_cvt_pk_bf16_f32 v13, v14, v15
	v_cvt_pk_bf16_f32 v63, v110, v111
	global_store_dwordx4 v[16:17], v[10:13], off
	global_store_dwordx4 v[122:123], v[60:63], off
	global_load_dwordx4 v[22:25], v[124:125], off nt
	global_load_dwordx2 v[78:79], v[126:127], off nt
	global_load_dwordx4 v[18:21], v[128:129], off nt
	global_load_dwordx2 v[64:65], v[130:131], off nt
	global_load_dwordx4 v[14:17], v[132:133], off nt
	global_load_dwordx2 v[62:63], v[134:135], off nt
	global_load_dwordx4 v[10:13], v[136:137], off nt
	global_load_dwordx2 v[60:61], v[138:139], off nt
	v_lshlrev_b32_e32 v34, 16, v6
	v_and_b32_e32 v6, 0xffff0000, v6
	v_mul_f32_e32 v6, 0x3fb8aa3b, v6
	v_exp_f32_e32 v35, v6
	v_lshlrev_b32_e32 v6, 16, v7
	v_and_b32_e32 v7, 0xffff0000, v7
	v_mul_f32_e32 v6, 0x3fb8aa3b, v6
	v_exp_f32_e32 v36, v6
	v_mul_f32_e32 v6, 0x3fb8aa3b, v7
	v_exp_f32_e32 v37, v6
	v_lshlrev_b32_e32 v6, 16, v8
	v_and_b32_e32 v7, 0xffff0000, v8
	v_mul_f32_e32 v6, 0x3fb8aa3b, v6
	v_exp_f32_e32 v114, v6
	v_mul_f32_e32 v6, 0x3fb8aa3b, v7
	v_exp_f32_e32 v115, v6
	v_lshlrev_b32_e32 v6, 16, v9
	v_and_b32_e32 v7, 0xffff0000, v9
	v_mul_f32_e32 v6, 0x3fb8aa3b, v6
	v_exp_f32_e32 v116, v6
	v_mul_f32_e32 v6, 0x3fb8aa3b, v7
	v_mul_f32_e32 v34, 0x3fb8aa3b, v34
	v_exp_f32_e32 v117, v6
	v_lshlrev_b32_e32 v6, 16, v2
	v_and_b32_e32 v2, 0xffff0000, v2
	v_lshl_add_u64 v[26:27], s[30:31], 0, v[76:77]
	v_cvt_pk_f32_fp8_e32 v[76:77], v58
	v_exp_f32_e32 v34, v34
	v_mul_f32_e32 v6, 0x3fb8aa3b, v6
	v_mul_f32_e32 v2, 0x3fb8aa3b, v2
	v_cvt_pk_f32_fp8_e32 v[8:9], v56
	v_cvt_pk_f32_fp8_sdwa v[120:121], v56 src0_sel:WORD_1
	v_cvt_pk_f32_fp8_e32 v[122:123], v57
	v_cvt_pk_f32_fp8_sdwa v[124:125], v57 src0_sel:WORD_1
	v_exp_f32_e32 v56, v6
	v_exp_f32_e32 v57, v2
	v_pk_fma_f32 v[6:7], v[140:141], v[106:107], v[100:101]
	v_lshl_add_u64 v[118:119], s[30:31], 0, v[54:55]
	v_cvt_pk_bf16_f32 v2, v6, v7
	v_pk_fma_f32 v[54:55], v[80:81], v[6:7], v[142:143]
	v_lshlrev_b32_e32 v7, 16, v3
	v_and_b32_e32 v3, 0xffff0000, v3
	v_cvt_pk_f32_fp8_sdwa v[152:153], v58 src0_sel:WORD_1
	v_pk_fma_f32 v[34:35], v[34:35], v[54:55], v[76:77]
	v_mul_f32_e32 v7, 0x3fb8aa3b, v7
	v_mul_f32_e32 v3, 0x3fb8aa3b, v3
	v_cvt_pk_bf16_f32 v6, v54, v55
	v_cvt_pk_bf16_f32 v54, v34, v35
	v_pk_fma_f32 v[34:35], v[56:57], v[34:35], v[8:9]
	v_exp_f32_e32 v8, v7
	v_exp_f32_e32 v9, v3
	v_pk_fma_f32 v[56:57], v[102:103], v[104:105], v[84:85]
	v_cvt_pk_f32_fp8_e32 v[112:113], v59
	v_cvt_pk_bf16_f32 v3, v56, v57
	v_pk_fma_f32 v[56:57], v[148:149], v[56:57], v[144:145]
	s_cmp_gt_u32 s5, 13
	v_pk_fma_f32 v[36:37], v[36:37], v[56:57], v[152:153]
	v_cvt_pk_bf16_f32 v7, v56, v57
	v_cvt_pk_bf16_f32 v55, v36, v37
	v_pk_fma_f32 v[36:37], v[8:9], v[36:37], v[120:121]
	v_lshlrev_b32_e32 v8, 16, v4
	v_and_b32_e32 v4, 0xffff0000, v4
	v_mul_f32_e32 v8, 0x3fb8aa3b, v8
	v_mul_f32_e32 v4, 0x3fb8aa3b, v4
	v_exp_f32_e32 v76, v8
	v_exp_f32_e32 v77, v4
	v_pk_fma_f32 v[8:9], v[98:99], v[108:109], v[38:39]
	v_lshl_add_u64 v[30:31], s[30:31], 0, v[66:67]
	v_pk_fma_f32 v[38:39], v[150:151], v[8:9], v[146:147]
	v_cvt_pk_bf16_f32 v4, v8, v9
	v_cvt_pk_bf16_f32 v8, v38, v39
	v_pk_fma_f32 v[38:39], v[114:115], v[38:39], v[112:113]
	v_lshlrev_b32_e32 v9, 16, v5
	v_and_b32_e32 v5, 0xffff0000, v5
	v_mul_f32_e32 v9, 0x3fb8aa3b, v9
	v_mul_f32_e32 v5, 0x3fb8aa3b, v5
	v_cvt_pk_bf16_f32 v56, v38, v39
	v_pk_fma_f32 v[38:39], v[76:77], v[38:39], v[122:123]
	v_cvt_pk_f32_fp8_sdwa v[58:59], v59 src0_sel:WORD_1
	v_cvt_pk_bf16_f32 v100, v34, v35
	v_cvt_pk_bf16_f32 v101, v36, v37
	v_exp_f32_e32 v80, v9
	v_exp_f32_e32 v81, v5
	v_cvt_pk_bf16_f32 v102, v38, v39
	v_pk_fma_f32 v[40:41], v[82:83], v[110:111], v[40:41]
	v_add_u32_e32 v42, 0x4000, v42
	v_cvt_pk_bf16_f32 v5, v40, v41
	global_store_dwordx4 v[30:31], v[2:5], off
	v_lshl_add_u64 v[74:75], v[74:75], 0, s[40:41]
	s_mov_b32 s5, s4
	v_pk_fma_f32 v[2:3], v[28:29], v[40:41], v[32:33]
	s_nop 0
	v_cvt_pk_bf16_f32 v9, v2, v3
	v_pk_fma_f32 v[2:3], v[116:117], v[2:3], v[58:59]
	global_store_dwordx4 v[26:27], v[6:9], off
	v_pk_fma_f32 v[40:41], v[80:81], v[2:3], v[124:125]
	v_cvt_pk_bf16_f32 v57, v2, v3
	v_cvt_pk_bf16_f32 v103, v40, v41
	v_lshl_add_u64 v[2:3], s[30:31], 0, v[44:45]
	global_store_dwordx4 v[118:119], v[54:57], off
	global_store_dwordx4 v[2:3], v[100:103], off
	s_cbranch_scc0 .LBB0_1724
	v_lshl_add_u64 v[2:3], s[30:31], 0, v[86:87]
	global_load_dwordx4 v[42:45], v[88:89], off
	s_nop 0
	global_load_dwordx2 v[88:89], v[96:97], off
	v_lshl_add_u64 v[4:5], s[26:27], 0, v[86:87]
	global_load_dwordx4 v[38:41], v[92:93], off
	global_load_dwordx4 v[30:33], v[2:3], off
	global_load_dwordx2 v[74:75], v[94:95], off
	v_lshl_add_u64 v[2:3], s[30:31], 0, v[90:91]
	s_waitcnt vmcnt(0) lgkmcnt(0)
	global_load_dwordx4 v[14:17], v[4:5], off
	global_load_dwordx4 v[6:9], v[2:3], off
	v_lshl_add_u64 v[2:3], s[26:27], 0, v[90:91]
	global_load_dwordx4 v[2:5], v[2:3], off
	v_add_u32_e32 v54, 0x1f800, v69
	v_lshl_add_u64 v[56:57], s[22:23], 0, v[72:73]
	s_mov_b32 s0, 0
	s_mov_b32 s4, 4
.LBB0_1726:
	v_add_u32_e32 v66, 0xfffff000, v54
	v_lshl_add_u64 v[10:11], s[20:21], 0, v[66:67]
	global_load_dwordx4 v[122:125], v[10:11], off
	v_lshl_add_u64 v[10:11], s[30:31], 0, v[66:67]
	v_lshl_add_u64 v[60:61], s[26:27], 0, v[66:67]
	v_add_u32_e32 v66, 0xffffe800, v54
	global_load_dwordx4 v[26:29], v[10:11], off
	global_load_dwordx4 v[22:25], v[60:61], off
	v_lshl_add_u64 v[10:11], s[20:21], 0, v[66:67]
	global_load_dwordx4 v[34:37], v[10:11], off
	global_load_dwordx2 v[62:63], v[56:57], off offset:1024 nt
	global_load_dwordx2 v[126:127], v[56:57], off nt
	v_lshl_add_u64 v[10:11], s[30:31], 0, v[66:67]
	v_lshl_add_u64 v[58:59], s[26:27], 0, v[66:67]
	global_load_dwordx4 v[18:21], v[10:11], off
	s_nop 0
	global_load_dwordx4 v[10:13], v[58:59], off
	s_waitcnt vmcnt(0) lgkmcnt(0)
	v_lshlrev_b32_e32 v55, 16, v42
	v_and_b32_e32 v42, 0xffff0000, v42
	v_mul_f32_e32 v42, 0x3fb8aa3b, v42
	v_exp_f32_e32 v131, v42
	v_lshlrev_b32_e32 v42, 16, v43
	v_and_b32_e32 v43, 0xffff0000, v43
	v_mul_f32_e32 v42, 0x3fb8aa3b, v42
	v_exp_f32_e32 v120, v42
	v_mul_f32_e32 v42, 0x3fb8aa3b, v43
	v_exp_f32_e32 v121, v42
	v_lshlrev_b32_e32 v42, 16, v44
	v_and_b32_e32 v43, 0xffff0000, v44
	v_mul_f32_e32 v42, 0x3fb8aa3b, v42
	v_exp_f32_e32 v106, v42
	v_mul_f32_e32 v42, 0x3fb8aa3b, v43
	v_exp_f32_e32 v107, v42
	v_lshlrev_b32_e32 v42, 16, v45
	v_mul_f32_e32 v55, 0x3fb8aa3b, v55
	v_and_b32_e32 v43, 0xffff0000, v45
	v_mul_f32_e32 v42, 0x3fb8aa3b, v42
	v_exp_f32_e32 v130, v55
	v_exp_f32_e32 v92, v42
	v_mul_f32_e32 v42, 0x3fb8aa3b, v43
	v_mov_b32_e32 v55, v67
	v_exp_f32_e32 v93, v42
	v_lshl_add_u64 v[42:43], s[26:27], 0, v[54:55]
	v_lshlrev_b32_e32 v55, 16, v38
	v_mul_f32_e32 v55, 0x3fb8aa3b, v55
	v_exp_f32_e32 v134, v55
	s_waitcnt vmcnt(0) lgkmcnt(0)
	v_lshlrev_b32_e32 v55, 16, v122
	v_cvt_pk_f32_fp8_e32 v[136:137], v62
	v_cvt_pk_f32_fp8_sdwa v[110:111], v62 src0_sel:WORD_1
	v_and_b32_e32 v62, 0xffff0000, v122
	v_mul_f32_e32 v55, 0x3fb8aa3b, v55
	v_exp_f32_e32 v138, v55
	v_mul_f32_e32 v55, 0x3fb8aa3b, v62
	v_exp_f32_e32 v139, v55
	v_lshlrev_b32_e32 v55, 16, v123
	v_and_b32_e32 v62, 0xffff0000, v123
	v_mul_f32_e32 v55, 0x3fb8aa3b, v55
	v_cvt_pk_f32_fp8_e32 v[128:129], v88
	s_add_i32 s5, s0, 2
	v_exp_f32_e32 v112, v55
	v_mul_f32_e32 v55, 0x3fb8aa3b, v62
	s_cmp_lt_u32 s0, 30
	v_exp_f32_e32 v113, v55
	v_lshlrev_b32_e32 v55, 16, v124
	s_cselect_b32 s1, s4, 62
	v_and_b32_e32 v62, 0xffff0000, v124
	v_mul_f32_e32 v55, 0x3fb8aa3b, v55
	s_sub_i32 s6, 63, s1
	v_exp_f32_e32 v98, v55
	v_mul_f32_e32 v55, 0x3fb8aa3b, v62
	s_sub_i32 s1, 62, s1
	v_lshl_add_u32 v64, s6, 10, v70
	v_mov_b32_e32 v65, v67
	v_exp_f32_e32 v99, v55
	v_lshlrev_b32_e32 v55, 16, v125
	v_pk_fma_f32 v[50:51], v[50:51], v[130:131], v[128:129]
	v_lshlrev_b32_e32 v128, 16, v14
	v_cvt_pk_f32_fp8_e32 v[132:133], v74
	v_cvt_pk_f32_fp8_sdwa v[114:115], v74 src0_sel:WORD_1
	v_cvt_pk_f32_fp8_e32 v[100:101], v75
	v_cvt_pk_f32_fp8_sdwa v[44:45], v75 src0_sel:WORD_1
	v_lshl_add_u64 v[74:75], s[28:29], 0, v[64:65]
	v_lshl_add_u32 v64, s1, 10, v70
	v_and_b32_e32 v62, 0xffff0000, v125
	v_mul_f32_e32 v55, 0x3fb8aa3b, v55
	v_and_b32_e32 v129, 0xffff0000, v14
	v_mul_f32_e32 v14, 0x3d372713, v128
	v_lshl_add_u64 v[82:83], s[28:29], 0, v[64:65]
	v_cvt_pk_f32_fp8_e32 v[96:97], v63
	v_cvt_pk_f32_fp8_sdwa v[64:65], v63 src0_sel:WORD_1
	v_exp_f32_e32 v72, v55
	v_mul_f32_e32 v55, 0x3fb8aa3b, v62
	v_cvt_pk_f32_fp8_e32 v[122:123], v126
	v_cvt_pk_f32_fp8_sdwa v[108:109], v126 src0_sel:WORD_1
	v_cvt_pk_f32_fp8_e32 v[94:95], v127
	v_cvt_pk_f32_fp8_sdwa v[62:63], v127 src0_sel:WORD_1
	v_lshlrev_b32_e32 v126, 16, v30
	v_and_b32_e32 v127, 0xffff0000, v30
	v_mul_f32_e32 v14, v14, v128
	v_mov_b32_e32 v30, v128
	v_fmac_f32_e32 v30, v14, v30
	v_mul_f32_e32 v14, 0x3f4c422a, v30
	v_add_f32_e32 v14, v14, v14
	v_mul_f32_e32 v14, 0x3fb8aa3b, v14
	v_exp_f32_e32 v14, v14
	v_mov_b32_e32 v30, v129
	v_pk_add_f32 v[126:127], v[50:51], v[126:127]
	v_and_b32_e32 v38, 0xffff0000, v38
	v_add_f32_e32 v14, 1.0, v14
	v_rcp_f32_e32 v130, v14
	v_mul_f32_e32 v14, 0x3d372713, v129
	v_mul_f32_e32 v14, v14, v129
	v_fmac_f32_e32 v30, v14, v30
	v_mul_f32_e32 v14, 0x3f4c422a, v30
	v_add_f32_e32 v14, v14, v14
	v_mul_f32_e32 v14, 0x3fb8aa3b, v14
	v_exp_f32_e32 v14, v14
	v_pk_mul_f32 v[128:129], v[128:129], 0.5 op_sel_hi:[1,0]
	v_pk_mul_f32 v[126:127], v[126:127], s[42:43] op_sel_hi:[1,0]
	v_mul_f32_e32 v38, 0x3fb8aa3b, v38
	v_add_f32_e32 v14, 1.0, v14
	v_rcp_f32_e32 v131, v14
	v_exp_f32_e32 v135, v38
	v_exp_f32_e32 v73, v55
	v_lshlrev_b32_e32 v55, 16, v34
	v_pk_fma_f32 v[130:131], v[130:131], 2.0, 1.0 op_sel_hi:[1,0,0] neg_lo:[1,0,0] neg_hi:[1,0,0]
	v_pk_fma_f32 v[50:51], v[134:135], v[50:51], v[132:133]
	v_pk_add_f32 v[130:131], v[130:131], 1.0 op_sel_hi:[1,0]
	v_and_b32_e32 v34, 0xffff0000, v34
	v_pk_mul_f32 v[128:129], v[128:129], v[130:131]
	v_mul_f32_e32 v55, 0x3fb8aa3b, v55
	v_pk_mul_f32 v[126:127], v[126:127], v[128:129]
	v_lshlrev_b32_e32 v128, 16, v2
	v_and_b32_e32 v129, 0xffff0000, v2
	v_mul_f32_e32 v2, 0x3d372713, v128
	v_cvt_pk_bf16_f32 v14, v126, v127
	v_lshlrev_b32_e32 v126, 16, v6
	v_and_b32_e32 v127, 0xffff0000, v6
	v_mul_f32_e32 v2, v2, v128
	v_mov_b32_e32 v6, v128
	v_fmac_f32_e32 v6, v2, v6
	v_mul_f32_e32 v2, 0x3f4c422a, v6
	v_add_f32_e32 v2, v2, v2
	v_mul_f32_e32 v2, 0x3fb8aa3b, v2
	v_exp_f32_e32 v2, v2
	v_mov_b32_e32 v6, v129
	v_pk_add_f32 v[126:127], v[50:51], v[126:127]
	v_mul_f32_e32 v34, 0x3fb8aa3b, v34
	v_add_f32_e32 v2, 1.0, v2
	v_rcp_f32_e32 v130, v2
	v_mul_f32_e32 v2, 0x3d372713, v129
	v_mul_f32_e32 v2, v2, v129
	v_fmac_f32_e32 v6, v2, v6
	v_mul_f32_e32 v2, 0x3f4c422a, v6
	v_add_f32_e32 v2, v2, v2
	v_mul_f32_e32 v2, 0x3fb8aa3b, v2
	v_exp_f32_e32 v2, v2
	v_pk_mul_f32 v[128:129], v[128:129], 0.5 op_sel_hi:[1,0]
	v_pk_mul_f32 v[126:127], v[126:127], s[42:43] op_sel_hi:[1,0]
	v_exp_f32_e32 v124, v55
	v_add_f32_e32 v2, 1.0, v2
	v_rcp_f32_e32 v131, v2
	v_exp_f32_e32 v125, v34
	v_pk_fma_f32 v[50:51], v[138:139], v[50:51], v[136:137]
	v_cvt_pk_f32_fp8_sdwa v[118:119], v88 src0_sel:WORD_1
	v_pk_fma_f32 v[130:131], v[130:131], 2.0, 1.0 op_sel_hi:[1,0,0] neg_lo:[1,0,0] neg_hi:[1,0,0]
	v_lshlrev_b32_e32 v38, 16, v39
	v_pk_add_f32 v[130:131], v[130:131], 1.0 op_sel_hi:[1,0]
	v_pk_fma_f32 v[48:49], v[48:49], v[120:121], v[118:119]
	v_pk_mul_f32 v[128:129], v[128:129], v[130:131]
	v_lshlrev_b32_e32 v118, 16, v15
	v_pk_mul_f32 v[126:127], v[128:129], v[126:127]
	v_lshlrev_b32_e32 v128, 16, v22
	v_mul_f32_e32 v6, 0x3d372713, v128
	v_and_b32_e32 v129, 0xffff0000, v22
	v_mul_f32_e32 v6, v6, v128
	v_mov_b32_e32 v22, v128
	v_fmac_f32_e32 v22, v6, v22
	v_mul_f32_e32 v6, 0x3f4c422a, v22
	v_add_f32_e32 v6, v6, v6
	v_mul_f32_e32 v6, 0x3fb8aa3b, v6
	v_exp_f32_e32 v6, v6
	v_mov_b32_e32 v22, v129
	v_cvt_pk_bf16_f32 v2, v126, v127
	v_lshlrev_b32_e32 v126, 16, v26
	v_add_f32_e32 v6, 1.0, v6
	v_rcp_f32_e32 v130, v6
	v_mul_f32_e32 v6, 0x3d372713, v129
	v_mul_f32_e32 v6, v6, v129
	v_fmac_f32_e32 v22, v6, v22
	v_mul_f32_e32 v6, 0x3f4c422a, v22
	v_add_f32_e32 v6, v6, v6
	v_mul_f32_e32 v6, 0x3fb8aa3b, v6
	v_exp_f32_e32 v6, v6
	v_and_b32_e32 v127, 0xffff0000, v26
	v_pk_add_f32 v[126:127], v[50:51], v[126:127]
	v_pk_fma_f32 v[50:51], v[124:125], v[50:51], v[122:123]
	v_add_f32_e32 v6, 1.0, v6
	v_lshlrev_b32_e32 v124, 16, v10
	v_rcp_f32_e32 v131, v6
	v_mul_f32_e32 v6, 0x3d372713, v124
	v_and_b32_e32 v125, 0xffff0000, v10
	v_mul_f32_e32 v6, v6, v124
	v_mov_b32_e32 v10, v124
	v_fmac_f32_e32 v10, v6, v10
	v_mul_f32_e32 v6, 0x3f4c422a, v10
	v_add_f32_e32 v6, v6, v6
	v_mul_f32_e32 v6, 0x3fb8aa3b, v6
	v_exp_f32_e32 v6, v6
	v_pk_fma_f32 v[130:131], v[130:131], 2.0, 1.0 op_sel_hi:[1,0,0] neg_lo:[1,0,0] neg_hi:[1,0,0]
	v_pk_mul_f32 v[128:129], v[128:129], 0.5 op_sel_hi:[1,0]
	v_pk_add_f32 v[130:131], v[130:131], 1.0 op_sel_hi:[1,0]
	v_pk_mul_f32 v[126:127], v[126:127], s[42:43] op_sel_hi:[1,0]
	v_pk_mul_f32 v[128:129], v[128:129], v[130:131]
	v_add_f32_e32 v6, 1.0, v6
	v_pk_mul_f32 v[126:127], v[128:129], v[126:127]
	v_mov_b32_e32 v10, v125
	v_cvt_pk_bf16_f32 v22, v126, v127
	v_rcp_f32_e32 v126, v6
	v_mul_f32_e32 v6, 0x3d372713, v125
	v_mul_f32_e32 v6, v6, v125
	v_fmac_f32_e32 v10, v6, v10
	v_mul_f32_e32 v6, 0x3f4c422a, v10
	v_add_f32_e32 v6, v6, v6
	v_mul_f32_e32 v6, 0x3fb8aa3b, v6
	v_exp_f32_e32 v6, v6
	v_lshlrev_b32_e32 v122, 16, v18
	v_and_b32_e32 v123, 0xffff0000, v18
	v_and_b32_e32 v18, 0xffff0000, v35
	v_add_f32_e32 v6, 1.0, v6
	v_rcp_f32_e32 v127, v6
	v_lshlrev_b32_e32 v6, 16, v35
	v_mul_f32_e32 v6, 0x3fb8aa3b, v6
	v_exp_f32_e32 v34, v6
	v_mul_f32_e32 v6, 0x3fb8aa3b, v18
	v_exp_f32_e32 v35, v6
	v_mul_f32_e32 v6, 0x3d372713, v118
	v_and_b32_e32 v119, 0xffff0000, v15
	v_mul_f32_e32 v6, v6, v118
	v_mov_b32_e32 v15, v118
	v_fmac_f32_e32 v15, v6, v15
	v_mul_f32_e32 v6, 0x3f4c422a, v15
	v_add_f32_e32 v6, v6, v6
	v_mul_f32_e32 v6, 0x3fb8aa3b, v6
	v_exp_f32_e32 v6, v6
	v_mov_b32_e32 v15, v119
	v_and_b32_e32 v39, 0xffff0000, v39
	v_mul_f32_e32 v38, 0x3fb8aa3b, v38
	v_add_f32_e32 v6, 1.0, v6
	v_rcp_f32_e32 v120, v6
	v_mul_f32_e32 v6, 0x3d372713, v119
	v_mul_f32_e32 v6, v6, v119
	v_fmac_f32_e32 v15, v6, v15
	v_mul_f32_e32 v6, 0x3f4c422a, v15
	v_add_f32_e32 v6, v6, v6
	v_mul_f32_e32 v6, 0x3fb8aa3b, v6
	v_exp_f32_e32 v6, v6
	v_exp_f32_e32 v116, v38
	v_mul_f32_e32 v38, 0x3fb8aa3b, v39
	v_exp_f32_e32 v117, v38
	v_add_f32_e32 v6, 1.0, v6
	v_rcp_f32_e32 v121, v6
	v_lshlrev_b32_e32 v30, 16, v31
	v_and_b32_e32 v31, 0xffff0000, v31
	v_pk_mul_f32 v[118:119], v[118:119], 0.5 op_sel_hi:[1,0]
	v_pk_fma_f32 v[120:121], v[120:121], 2.0, 1.0 op_sel_hi:[1,0,0] neg_lo:[1,0,0] neg_hi:[1,0,0]
	v_pk_add_f32 v[30:31], v[48:49], v[30:31]
	v_pk_add_f32 v[120:121], v[120:121], 1.0 op_sel_hi:[1,0]
	v_pk_mul_f32 v[30:31], v[30:31], s[42:43] op_sel_hi:[1,0]
	v_pk_mul_f32 v[118:119], v[118:119], v[120:121]
	v_lshlrev_b32_e32 v6, 16, v7
	v_pk_mul_f32 v[30:31], v[118:119], v[30:31]
	v_and_b32_e32 v7, 0xffff0000, v7
	v_cvt_pk_bf16_f32 v15, v30, v31
	v_pk_fma_f32 v[30:31], v[116:117], v[48:49], v[114:115]
	v_lshlrev_b32_e32 v48, 16, v3
	v_and_b32_e32 v49, 0xffff0000, v3
	v_mul_f32_e32 v3, 0x3d372713, v48
	v_mul_f32_e32 v3, v3, v48
	v_mov_b32_e32 v18, v48
	v_fmac_f32_e32 v18, v3, v18
	v_mul_f32_e32 v3, 0x3f4c422a, v18
	v_add_f32_e32 v3, v3, v3
	v_mul_f32_e32 v3, 0x3fb8aa3b, v3
	v_exp_f32_e32 v3, v3
	v_mov_b32_e32 v18, v49
	v_pk_add_f32 v[6:7], v[30:31], v[6:7]
	v_lshlrev_b32_e32 v26, 16, v27
	v_add_f32_e32 v3, 1.0, v3
	v_rcp_f32_e32 v114, v3
	v_mul_f32_e32 v3, 0x3d372713, v49
	v_mul_f32_e32 v3, v3, v49
	v_fmac_f32_e32 v18, v3, v18
	v_mul_f32_e32 v3, 0x3f4c422a, v18
	v_add_f32_e32 v3, v3, v3
	v_mul_f32_e32 v3, 0x3fb8aa3b, v3
	v_exp_f32_e32 v3, v3
	v_pk_mul_f32 v[48:49], v[48:49], 0.5 op_sel_hi:[1,0]
	v_pk_mul_f32 v[6:7], v[6:7], s[42:43] op_sel_hi:[1,0]
	v_and_b32_e32 v27, 0xffff0000, v27
	v_add_f32_e32 v3, 1.0, v3
	v_rcp_f32_e32 v115, v3
	v_cvt_pk_f32_fp8_e32 v[104:105], v89
	v_lshlrev_b32_e32 v38, 16, v40
	v_and_b32_e32 v39, 0xffff0000, v40
	v_pk_fma_f32 v[114:115], v[114:115], 2.0, 1.0 op_sel_hi:[1,0,0] neg_lo:[1,0,0] neg_hi:[1,0,0]
	v_mul_f32_e32 v38, 0x3fb8aa3b, v38
	v_pk_add_f32 v[114:115], v[114:115], 1.0 op_sel_hi:[1,0]
	v_exp_f32_e32 v102, v38
	v_pk_mul_f32 v[48:49], v[48:49], v[114:115]
	v_mul_f32_e32 v38, 0x3fb8aa3b, v39
	v_pk_mul_f32 v[6:7], v[48:49], v[6:7]
	v_exp_f32_e32 v103, v38
	v_cvt_pk_bf16_f32 v3, v6, v7
	v_pk_fma_f32 v[6:7], v[112:113], v[30:31], v[110:111]
	v_lshlrev_b32_e32 v30, 16, v23
	v_mul_f32_e32 v18, 0x3d372713, v30
	v_and_b32_e32 v31, 0xffff0000, v23
	v_mul_f32_e32 v18, v18, v30
	v_mov_b32_e32 v23, v30
	v_fmac_f32_e32 v23, v18, v23
	v_mul_f32_e32 v18, 0x3f4c422a, v23
	v_add_f32_e32 v18, v18, v18
	v_mul_f32_e32 v18, 0x3fb8aa3b, v18
	v_exp_f32_e32 v18, v18
	v_mov_b32_e32 v23, v31
	v_pk_add_f32 v[26:27], v[6:7], v[26:27]
	v_cvt_pk_f32_fp8_sdwa v[90:91], v89 src0_sel:WORD_1
	v_add_f32_e32 v18, 1.0, v18
	v_rcp_f32_e32 v48, v18
	v_mul_f32_e32 v18, 0x3d372713, v31
	v_mul_f32_e32 v18, v18, v31
	v_fmac_f32_e32 v23, v18, v23
	v_mul_f32_e32 v18, 0x3f4c422a, v23
	v_add_f32_e32 v18, v18, v18
	v_mul_f32_e32 v18, 0x3fb8aa3b, v18
	v_exp_f32_e32 v18, v18
	v_pk_mul_f32 v[30:31], v[30:31], 0.5 op_sel_hi:[1,0]
	v_pk_mul_f32 v[26:27], v[26:27], s[42:43] op_sel_hi:[1,0]
	v_lshlrev_b32_e32 v38, 16, v41
	v_add_f32_e32 v18, 1.0, v18
	v_rcp_f32_e32 v49, v18
	v_lshlrev_b32_e32 v18, 16, v11
	v_and_b32_e32 v39, 0xffff0000, v41
	v_mul_f32_e32 v38, 0x3fb8aa3b, v38
	v_pk_fma_f32 v[48:49], v[48:49], 2.0, 1.0 op_sel_hi:[1,0,0] neg_lo:[1,0,0] neg_hi:[1,0,0]
	v_exp_f32_e32 v88, v38
	v_pk_add_f32 v[48:49], v[48:49], 1.0 op_sel_hi:[1,0]
	v_mul_f32_e32 v38, 0x3fb8aa3b, v39
	v_pk_mul_f32 v[30:31], v[30:31], v[48:49]
	v_pk_fma_f32 v[48:49], v[34:35], v[6:7], v[108:109]
	v_pk_mul_f32 v[26:27], v[30:31], v[26:27]
	v_lshlrev_b32_e32 v6, 16, v19
	v_and_b32_e32 v7, 0xffff0000, v19
	v_and_b32_e32 v19, 0xffff0000, v11
	v_mul_f32_e32 v11, 0x3d372713, v18
	v_cvt_pk_bf16_f32 v23, v26, v27
	v_mul_f32_e32 v11, v11, v18
	v_mov_b32_e32 v26, v18
	v_fmac_f32_e32 v26, v11, v26
	v_mul_f32_e32 v11, 0x3f4c422a, v26
	v_add_f32_e32 v11, v11, v11
	v_mul_f32_e32 v11, 0x3fb8aa3b, v11
	v_exp_f32_e32 v11, v11
	v_mov_b32_e32 v27, v19
	v_lshlrev_b32_e32 v30, 16, v16
	v_and_b32_e32 v31, 0xffff0000, v16
	v_add_f32_e32 v11, 1.0, v11
	v_rcp_f32_e32 v26, v11
	v_mul_f32_e32 v11, 0x3d372713, v19
	v_mul_f32_e32 v11, v11, v19
	v_fmac_f32_e32 v27, v11, v27
	v_mul_f32_e32 v11, 0x3f4c422a, v27
	v_add_f32_e32 v11, v11, v11
	v_mul_f32_e32 v11, 0x3fb8aa3b, v11
	v_exp_f32_e32 v11, v11
	v_pk_mul_f32 v[18:19], v[18:19], 0.5 op_sel_hi:[1,0]
	v_mul_f32_e32 v16, 0x3d372713, v30
	v_mul_f32_e32 v16, v16, v30
	v_add_f32_e32 v11, 1.0, v11
	v_rcp_f32_e32 v27, v11
	v_pk_add_f32 v[6:7], v[48:49], v[6:7]
	v_exp_f32_e32 v89, v38
	v_pk_mul_f32 v[6:7], v[6:7], s[42:43] op_sel_hi:[1,0]
	v_pk_fma_f32 v[26:27], v[26:27], 2.0, 1.0 op_sel_hi:[1,0,0] neg_lo:[1,0,0] neg_hi:[1,0,0]
	v_add_u32_e32 v66, 0xfffff800, v54
	v_pk_add_f32 v[26:27], v[26:27], 1.0 op_sel_hi:[1,0]
	v_lshl_add_u64 v[38:39], s[26:27], 0, v[66:67]
	v_pk_mul_f32 v[18:19], v[18:19], v[26:27]
	v_lshlrev_b32_e32 v26, 16, v32
	v_and_b32_e32 v27, 0xffff0000, v32
	v_mov_b32_e32 v32, v30
	v_fmac_f32_e32 v32, v16, v32
	v_mul_f32_e32 v16, 0x3f4c422a, v32
	v_add_f32_e32 v16, v16, v16
	v_mul_f32_e32 v16, 0x3fb8aa3b, v16
	v_exp_f32_e32 v16, v16
	v_mov_b32_e32 v32, v31
	v_pk_mul_f32 v[6:7], v[18:19], v[6:7]
	v_pk_fma_f32 v[18:19], v[46:47], v[106:107], v[104:105]
	v_add_f32_e32 v16, 1.0, v16
	v_rcp_f32_e32 v34, v16
	v_mul_f32_e32 v16, 0x3d372713, v31
	v_mul_f32_e32 v16, v16, v31
	v_fmac_f32_e32 v32, v16, v32
	v_mul_f32_e32 v16, 0x3f4c422a, v32
	v_add_f32_e32 v16, v16, v16
	v_mul_f32_e32 v16, 0x3fb8aa3b, v16
	v_exp_f32_e32 v16, v16
	v_pk_mul_f32 v[30:31], v[30:31], 0.5 op_sel_hi:[1,0]
	v_pk_add_f32 v[26:27], v[18:19], v[26:27]
	v_pk_fma_f32 v[18:19], v[102:103], v[18:19], v[100:101]
	v_add_f32_e32 v16, 1.0, v16
	v_rcp_f32_e32 v35, v16
	v_pk_mul_f32 v[26:27], v[26:27], s[42:43] op_sel_hi:[1,0]
	v_cvt_pk_bf16_f32 v11, v6, v7
	v_lshlrev_b32_e32 v6, 16, v36
	v_pk_fma_f32 v[34:35], v[34:35], 2.0, 1.0 op_sel_hi:[1,0,0] neg_lo:[1,0,0] neg_hi:[1,0,0]
	v_and_b32_e32 v7, 0xffff0000, v36
	v_pk_add_f32 v[34:35], v[34:35], 1.0 op_sel_hi:[1,0]
	v_mul_f32_e32 v6, 0x3fb8aa3b, v6
	v_pk_mul_f32 v[30:31], v[30:31], v[34:35]
	v_mul_f32_e32 v7, 0x3fb8aa3b, v7
	v_pk_mul_f32 v[26:27], v[30:31], v[26:27]
	v_lshlrev_b32_e32 v30, 16, v4
	v_and_b32_e32 v31, 0xffff0000, v4
	v_mul_f32_e32 v4, 0x3d372713, v30
	v_cvt_pk_bf16_f32 v16, v26, v27
	v_lshlrev_b32_e32 v26, 16, v8
	v_and_b32_e32 v27, 0xffff0000, v8
	v_mul_f32_e32 v4, v4, v30
	v_mov_b32_e32 v8, v30
	v_fmac_f32_e32 v8, v4, v8
	v_mul_f32_e32 v4, 0x3f4c422a, v8
	v_add_f32_e32 v4, v4, v4
	v_mul_f32_e32 v4, 0x3fb8aa3b, v4
	v_exp_f32_e32 v4, v4
	v_mov_b32_e32 v8, v31
	v_pk_add_f32 v[26:27], v[18:19], v[26:27]
	v_exp_f32_e32 v6, v6
	v_add_f32_e32 v4, 1.0, v4
	v_rcp_f32_e32 v34, v4
	v_mul_f32_e32 v4, 0x3d372713, v31
	v_mul_f32_e32 v4, v4, v31
	v_fmac_f32_e32 v8, v4, v8
	v_mul_f32_e32 v4, 0x3f4c422a, v8
	v_add_f32_e32 v4, v4, v4
	v_mul_f32_e32 v4, 0x3fb8aa3b, v4
	v_exp_f32_e32 v4, v4
	v_pk_mul_f32 v[30:31], v[30:31], 0.5 op_sel_hi:[1,0]
	v_pk_mul_f32 v[26:27], v[26:27], s[42:43] op_sel_hi:[1,0]
	v_exp_f32_e32 v7, v7
	v_add_f32_e32 v4, 1.0, v4
	v_rcp_f32_e32 v35, v4
	v_pk_fma_f32 v[18:19], v[98:99], v[18:19], v[96:97]
	v_lshl_add_u32 v66, s6, 11, v68
	v_pk_fma_f32 v[46:47], v[6:7], v[18:19], v[94:95]
	v_pk_fma_f32 v[34:35], v[34:35], 2.0, 1.0 op_sel_hi:[1,0,0] neg_lo:[1,0,0] neg_hi:[1,0,0]
	v_lshlrev_b32_e32 v6, 16, v20
	v_pk_add_f32 v[34:35], v[34:35], 1.0 op_sel_hi:[1,0]
	v_and_b32_e32 v7, 0xffff0000, v20
	v_pk_mul_f32 v[30:31], v[30:31], v[34:35]
	v_pk_add_f32 v[6:7], v[46:47], v[6:7]
	v_pk_mul_f32 v[26:27], v[30:31], v[26:27]
	v_lshlrev_b32_e32 v30, 16, v24
	v_mul_f32_e32 v8, 0x3d372713, v30
	v_and_b32_e32 v31, 0xffff0000, v24
	v_mul_f32_e32 v8, v8, v30
	v_mov_b32_e32 v24, v30
	v_fmac_f32_e32 v24, v8, v24
	v_mul_f32_e32 v8, 0x3f4c422a, v24
	v_add_f32_e32 v8, v8, v8
	v_mul_f32_e32 v8, 0x3fb8aa3b, v8
	v_exp_f32_e32 v8, v8
	v_mov_b32_e32 v24, v31
	v_cvt_pk_bf16_f32 v4, v26, v27
	v_lshlrev_b32_e32 v26, 16, v28
	v_add_f32_e32 v8, 1.0, v8
	v_rcp_f32_e32 v34, v8
	v_mul_f32_e32 v8, 0x3d372713, v31
	v_mul_f32_e32 v8, v8, v31
	v_fmac_f32_e32 v24, v8, v24
	v_mul_f32_e32 v8, 0x3f4c422a, v24
	v_add_f32_e32 v8, v8, v8
	v_mul_f32_e32 v8, 0x3fb8aa3b, v8
	v_exp_f32_e32 v8, v8
	v_and_b32_e32 v27, 0xffff0000, v28
	v_pk_add_f32 v[26:27], v[18:19], v[26:27]
	v_lshlrev_b32_e32 v18, 16, v12
	v_add_f32_e32 v8, 1.0, v8
	v_rcp_f32_e32 v35, v8
	v_mul_f32_e32 v8, 0x3d372713, v18
	v_and_b32_e32 v19, 0xffff0000, v12
	v_mul_f32_e32 v8, v8, v18
	v_mov_b32_e32 v12, v18
	v_fmac_f32_e32 v12, v8, v12
	v_mul_f32_e32 v8, 0x3f4c422a, v12
	v_add_f32_e32 v8, v8, v8
	v_mul_f32_e32 v8, 0x3fb8aa3b, v8
	v_exp_f32_e32 v8, v8
	v_pk_fma_f32 v[34:35], v[34:35], 2.0, 1.0 op_sel_hi:[1,0,0] neg_lo:[1,0,0] neg_hi:[1,0,0]
	v_pk_mul_f32 v[30:31], v[30:31], 0.5 op_sel_hi:[1,0]
	v_pk_add_f32 v[34:35], v[34:35], 1.0 op_sel_hi:[1,0]
	v_pk_mul_f32 v[26:27], v[26:27], s[42:43] op_sel_hi:[1,0]
	v_pk_mul_f32 v[30:31], v[30:31], v[34:35]
	v_add_f32_e32 v8, 1.0, v8
	v_pk_mul_f32 v[26:27], v[30:31], v[26:27]
	v_mov_b32_e32 v12, v19
	v_cvt_pk_bf16_f32 v24, v26, v27
	v_rcp_f32_e32 v26, v8
	v_mul_f32_e32 v8, 0x3d372713, v19
	v_mul_f32_e32 v8, v8, v19
	v_fmac_f32_e32 v12, v8, v12
	v_mul_f32_e32 v8, 0x3f4c422a, v12
	v_add_f32_e32 v8, v8, v8
	v_mul_f32_e32 v8, 0x3fb8aa3b, v8
	v_exp_f32_e32 v8, v8
	v_lshlrev_b32_e32 v30, 16, v17
	v_and_b32_e32 v31, 0xffff0000, v17
	v_mov_b32_e32 v17, v30
	v_add_f32_e32 v8, 1.0, v8
	v_rcp_f32_e32 v27, v8
	v_mul_f32_e32 v8, 0x3d372713, v30
	v_mul_f32_e32 v8, v8, v30
	v_fmac_f32_e32 v17, v8, v17
	v_mul_f32_e32 v8, 0x3f4c422a, v17
	v_add_f32_e32 v8, v8, v8
	v_mul_f32_e32 v8, 0x3fb8aa3b, v8
	v_exp_f32_e32 v8, v8
	v_mov_b32_e32 v17, v31
	v_pk_fma_f32 v[26:27], v[26:27], 2.0, 1.0 op_sel_hi:[1,0,0] neg_lo:[1,0,0] neg_hi:[1,0,0]
	v_pk_mul_f32 v[18:19], v[18:19], 0.5 op_sel_hi:[1,0]
	v_add_f32_e32 v8, 1.0, v8
	v_rcp_f32_e32 v32, v8
	v_mul_f32_e32 v8, 0x3d372713, v31
	v_mul_f32_e32 v8, v8, v31
	v_fmac_f32_e32 v17, v8, v17
	v_mul_f32_e32 v8, 0x3f4c422a, v17
	v_add_f32_e32 v8, v8, v8
	v_mul_f32_e32 v8, 0x3fb8aa3b, v8
	v_exp_f32_e32 v8, v8
	v_pk_add_f32 v[26:27], v[26:27], 1.0 op_sel_hi:[1,0]
	v_pk_mul_f32 v[6:7], v[6:7], s[42:43] op_sel_hi:[1,0]
	v_pk_mul_f32 v[18:19], v[18:19], v[26:27]
	v_add_f32_e32 v8, 1.0, v8
	v_pk_mul_f32 v[6:7], v[18:19], v[6:7]
	v_lshlrev_b32_e32 v26, 16, v33
	v_and_b32_e32 v27, 0xffff0000, v33
	v_rcp_f32_e32 v33, v8
	v_cvt_pk_bf16_f32 v12, v6, v7
	v_lshlrev_b32_e32 v6, 16, v37
	v_and_b32_e32 v7, 0xffff0000, v37
	v_mul_f32_e32 v6, 0x3fb8aa3b, v6
	v_exp_f32_e32 v18, v6
	v_mul_f32_e32 v6, 0x3fb8aa3b, v7
	v_exp_f32_e32 v19, v6
	v_pk_fma_f32 v[6:7], v[52:53], v[92:93], v[90:91]
	v_pk_fma_f32 v[32:33], v[32:33], 2.0, 1.0 op_sel_hi:[1,0,0] neg_lo:[1,0,0] neg_hi:[1,0,0]
	v_pk_mul_f32 v[30:31], v[30:31], 0.5 op_sel_hi:[1,0]
	v_pk_add_f32 v[32:33], v[32:33], 1.0 op_sel_hi:[1,0]
	v_pk_add_f32 v[26:27], v[6:7], v[26:27]
	v_pk_mul_f32 v[30:31], v[30:31], v[32:33]
	v_pk_mul_f32 v[26:27], v[26:27], s[42:43] op_sel_hi:[1,0]
	v_lshlrev_b32_e32 v8, 16, v5
	v_pk_mul_f32 v[26:27], v[30:31], v[26:27]
	v_lshl_add_u64 v[40:41], s[20:21], 0, v[66:67]
	v_cvt_pk_bf16_f32 v17, v26, v27
	v_pk_fma_f32 v[26:27], v[88:89], v[6:7], v[44:45]
	v_lshlrev_b32_e32 v6, 16, v9
	v_and_b32_e32 v7, 0xffff0000, v9
	v_and_b32_e32 v9, 0xffff0000, v5
	v_mul_f32_e32 v5, 0x3d372713, v8
	global_store_dwordx4 v[42:43], v[14:17], off
	v_mul_f32_e32 v5, v5, v8
	v_pk_add_f32 v[6:7], v[26:27], v[6:7]
	v_mov_b32_e32 v14, v8
	v_fmac_f32_e32 v14, v5, v14
	v_mul_f32_e32 v5, 0x3f4c422a, v14
	v_add_f32_e32 v5, v5, v5
	v_mul_f32_e32 v5, 0x3fb8aa3b, v5
	v_exp_f32_e32 v5, v5
	v_mov_b32_e32 v15, v9
	v_pk_mul_f32 v[6:7], v[6:7], s[42:43] op_sel_hi:[1,0]
	v_lshl_add_u64 v[76:77], s[30:31], 0, v[66:67]
	v_add_f32_e32 v5, 1.0, v5
	v_rcp_f32_e32 v14, v5
	v_mul_f32_e32 v5, 0x3d372713, v9
	v_mul_f32_e32 v5, v5, v9
	v_fmac_f32_e32 v15, v5, v15
	v_mul_f32_e32 v5, 0x3f4c422a, v15
	v_add_f32_e32 v5, v5, v5
	v_mul_f32_e32 v5, 0x3fb8aa3b, v5
	v_exp_f32_e32 v5, v5
	v_pk_mul_f32 v[8:9], v[8:9], 0.5 op_sel_hi:[1,0]
	v_lshl_add_u64 v[78:79], s[26:27], 0, v[66:67]
	v_lshl_add_u32 v66, s1, 11, v68
	v_add_f32_e32 v5, 1.0, v5
	v_rcp_f32_e32 v15, v5
	v_lshl_add_u64 v[80:81], s[20:21], 0, v[66:67]
	v_lshl_add_u64 v[84:85], s[30:31], 0, v[66:67]
	v_lshl_add_u64 v[86:87], s[26:27], 0, v[66:67]
	v_pk_fma_f32 v[14:15], v[14:15], 2.0, 1.0 op_sel_hi:[1,0,0] neg_lo:[1,0,0] neg_hi:[1,0,0]
	v_pk_fma_f32 v[126:127], v[126:127], 2.0, 1.0 op_sel_hi:[1,0,0] neg_lo:[1,0,0] neg_hi:[1,0,0]
	v_pk_add_f32 v[14:15], v[14:15], 1.0 op_sel_hi:[1,0]
	v_pk_mul_f32 v[124:125], v[124:125], 0.5 op_sel_hi:[1,0]
	v_pk_mul_f32 v[8:9], v[8:9], v[14:15]
	v_pk_add_f32 v[126:127], v[126:127], 1.0 op_sel_hi:[1,0]
	v_pk_mul_f32 v[6:7], v[8:9], v[6:7]
	v_pk_add_f32 v[122:123], v[50:51], v[122:123]
	v_cvt_pk_bf16_f32 v5, v6, v7
	global_store_dwordx4 v[38:39], v[2:5], off
	global_load_dwordx4 v[42:45], v[40:41], off
	global_load_dwordx2 v[88:89], v[74:75], off nt
	global_load_dwordx4 v[30:33], v[76:77], off
	global_load_dwordx4 v[14:17], v[78:79], off
	s_nop 0
	global_load_dwordx4 v[38:41], v[80:81], off
	global_load_dwordx2 v[74:75], v[82:83], off nt
	global_load_dwordx4 v[6:9], v[84:85], off
	global_load_dwordx4 v[2:5], v[86:87], off
	v_pk_mul_f32 v[124:125], v[124:125], v[126:127]
	v_pk_mul_f32 v[122:123], v[122:123], s[42:43] op_sel_hi:[1,0]
	s_add_i32 s4, s4, 4
	v_pk_mul_f32 v[122:123], v[124:125], v[122:123]
	s_cmp_gt_u32 s0, 29
	v_cvt_pk_bf16_f32 v10, v122, v123
	v_lshlrev_b32_e32 v34, 16, v25
	v_mul_f32_e32 v20, 0x3d372713, v34
	v_and_b32_e32 v35, 0xffff0000, v25
	v_mul_f32_e32 v20, v20, v34
	v_mov_b32_e32 v25, v34
	v_fmac_f32_e32 v25, v20, v25
	v_mul_f32_e32 v20, 0x3f4c422a, v25
	v_add_f32_e32 v20, v20, v20
	v_mul_f32_e32 v20, 0x3fb8aa3b, v20
	v_exp_f32_e32 v20, v20
	v_mov_b32_e32 v25, v35
	v_pk_fma_f32 v[26:27], v[72:73], v[26:27], v[64:65]
	v_lshlrev_b32_e32 v28, 16, v29
	v_add_f32_e32 v20, 1.0, v20
	v_rcp_f32_e32 v36, v20
	v_mul_f32_e32 v20, 0x3d372713, v35
	v_mul_f32_e32 v20, v20, v35
	v_fmac_f32_e32 v25, v20, v25
	v_mul_f32_e32 v20, 0x3f4c422a, v25
	v_add_f32_e32 v20, v20, v20
	v_mul_f32_e32 v20, 0x3fb8aa3b, v20
	v_exp_f32_e32 v20, v20
	v_and_b32_e32 v29, 0xffff0000, v29
	v_pk_mul_f32 v[34:35], v[34:35], 0.5 op_sel_hi:[1,0]
	v_pk_add_f32 v[28:29], v[26:27], v[28:29]
	v_add_f32_e32 v20, 1.0, v20
	v_rcp_f32_e32 v37, v20
	v_pk_mul_f32 v[28:29], v[28:29], s[42:43] op_sel_hi:[1,0]
	v_lshlrev_b32_e32 v20, 16, v13
	v_pk_fma_f32 v[52:53], v[18:19], v[26:27], v[62:63]
	v_pk_fma_f32 v[36:37], v[36:37], 2.0, 1.0 op_sel_hi:[1,0,0] neg_lo:[1,0,0] neg_hi:[1,0,0]
	v_lshlrev_b32_e32 v18, 16, v21
	v_pk_add_f32 v[36:37], v[36:37], 1.0 op_sel_hi:[1,0]
	v_and_b32_e32 v19, 0xffff0000, v21
	v_pk_mul_f32 v[34:35], v[34:35], v[36:37]
	v_and_b32_e32 v21, 0xffff0000, v13
	v_pk_mul_f32 v[28:29], v[34:35], v[28:29]
	v_mul_f32_e32 v13, 0x3d372713, v20
	v_cvt_pk_bf16_f32 v25, v28, v29
	global_store_dwordx4 v[60:61], v[22:25], off
	v_mul_f32_e32 v13, v13, v20
	v_pk_add_f32 v[18:19], v[52:53], v[18:19]
	v_mov_b32_e32 v22, v20
	v_fmac_f32_e32 v22, v13, v22
	v_mul_f32_e32 v13, 0x3f4c422a, v22
	v_add_f32_e32 v13, v13, v13
	v_mul_f32_e32 v13, 0x3fb8aa3b, v13
	v_exp_f32_e32 v13, v13
	v_mov_b32_e32 v23, v21
	v_pk_mul_f32 v[18:19], v[18:19], s[42:43] op_sel_hi:[1,0]
	s_movk_i32 s0, 0xf000
	v_add_f32_e32 v13, 1.0, v13
	v_rcp_f32_e32 v22, v13
	v_mul_f32_e32 v13, 0x3d372713, v21
	v_mul_f32_e32 v13, v13, v21
	v_fmac_f32_e32 v23, v13, v23
	v_mul_f32_e32 v13, 0x3f4c422a, v23
	v_add_f32_e32 v13, v13, v13
	v_mul_f32_e32 v13, 0x3fb8aa3b, v13
	v_exp_f32_e32 v13, v13
	v_pk_mul_f32 v[20:21], v[20:21], 0.5 op_sel_hi:[1,0]
	s_mov_b32 s1, -1
	v_add_u32_e32 v54, 0xffffe000, v54
	v_add_f32_e32 v13, 1.0, v13
	v_rcp_f32_e32 v23, v13
	v_lshl_add_u64 v[56:57], v[56:57], 0, s[0:1]
	s_mov_b32 s0, s5
	v_pk_fma_f32 v[22:23], v[22:23], 2.0, 1.0 op_sel_hi:[1,0,0] neg_lo:[1,0,0] neg_hi:[1,0,0]
	s_nop 0
	v_pk_add_f32 v[22:23], v[22:23], 1.0 op_sel_hi:[1,0]
	s_nop 0
	v_pk_mul_f32 v[20:21], v[20:21], v[22:23]
	s_nop 0
	v_pk_mul_f32 v[18:19], v[20:21], v[18:19]
	s_nop 0
	v_cvt_pk_bf16_f32 v13, v18, v19
	global_store_dwordx4 v[58:59], v[10:13], off
	s_cbranch_scc0 .LBB0_1726
	s_add_i32 s52, s52, s74
	s_add_i32 s50, s50, s51
	s_cmpk_gt_i32 s52, 0xff
	s_waitcnt lgkmcnt(0)
	s_barrier
	s_cbranch_scc0 .LBB0_1705
